# hand-written diff_prep + mla_prep (wide accesses, loads hoisted)
# speedup vs baseline: 1.0395x; 1.0094x over previous
; __device__ __forceinline__ int tid_() { int t = threadIdx.x; asm volatile("" : "+v"(t)); return t; }
; __device__ __forceinline__ float bf2f(bf16_t b) { return __uint_as_float(((unsigned)b) << 16); }
; __device__ __forceinline__ bf16_t f2bf(float f) { return (bf16_t)(cvt_pk_bf16(f, 0.f) & 0xffffu); }
; __device__ __forceinline__ float rope_lane(float x, int lane, int t, const float* __restrict__ ROPE) {
;   const int ax = lane >> 5, i = lane & 15, pos = ax ? (t & 63) : (t >> 6);
;   const float cs = ROPE[pos * 32 + i * 2], sn = ROPE[pos * 32 + i * 2 + 1];
;   const float pr = __shfl_xor(x, 16, 64);
;   return (lane & 16) ? (x * cs + pr * sn) : (x * cs - pr * sn);
; }
; __device__ __forceinline__ void diff_prep(bf16_t* __restrict__ DQK, const float* __restrict__ wq, const float* __restrict__ wk, const float* __restrict__ ROPE) {
;   const int tid = tid_(); const int wid = tid >> 6, lane = tid & 63; const float w_q = wq[lane], w_k = wk[lane];
;   const int stride = gridDim.x * 8;
;   for (int r0 = blockIdx.x * 8 + wid; r0 < T_TOK; r0 += 2 * stride) {
;     const int r1 = r0 + stride; const bool has1 = r1 < T_TOK;
;     bf16_t* p0 = DQK + (size_t)r0 * 1024; bf16_t* p1 = DQK + (size_t)(has1 ? r1 : r0) * 1024;
;     float x0[16], x1[16];
; #pragma unroll
;     for (int g = 0; g < 16; ++g) { x0[g] = bf2f(p0[g * 64 + lane]); x1[g] = bf2f(p1[g * 64 + lane]); }
; #pragma unroll
;     for (int g = 0; g < 16; ++g) {
;       const float s0 = wave_sum(x0[g] * x0[g]), s1 = wave_sum(x1[g] * x1[g]);
;       float y0 = x0[g] * rsqrtf(s0 * (1.f / 64.f) + EPSN) * (g < 8 ? w_q : w_k), y1 = x1[g] * rsqrtf(s1 * (1.f / 64.f) + EPSN) * (g < 8 ? w_q : w_k);
;       if (r0 >= NCTX) y0 = rope_lane(y0, lane, r0 - NCTX, ROPE);
;       if (r1 >= NCTX) y1 = rope_lane(y1, lane, r1 - NCTX, ROPE);
;       p0[g * 64 + lane] = f2bf(y0); if (has1) p1[g * 64 + lane] = f2bf(y1);
;     }
;   }
; }
.LBB0_1102:
	s_or_b64 exec, exec, s[12:13]
	s_mov_b32 s39, 0xbfb8aa3b
	s_mov_b32 s44, 0x42ce8ed0
	s_mov_b32 s45, 0xc2b17218
	s_mov_b32 s76, 0x3f2aaaab
	s_mov_b32 s77, 0x3f317218
	s_mov_b32 s78, 0x33800000
	s_load_dwordx2 s[6:7], s[0:1], 0xd8
	s_load_dwordx2 s[8:9], s[0:1], 0xa8
	s_load_dwordx2 s[10:11], s[0:1], 0xb0
	v_and_b32_e32 v0, 63, v187
	v_lshlrev_b32_e32 v1, 4, v0
	v_and_b32_e32 v2, 7, v0
	v_lshlrev_b32_e32 v2, 5, v2
	s_lshl_b32 s12, s34, 8
	v_add_u32_e32 v2, s12, v2
	v_and_b32_e32 v3, 1, v0
	v_lshlrev_b32_e32 v3, 6, v3
	v_readfirstlane_b32 s17, v187
	s_nop 3
	s_lshr_b32 s17, s17, 6
	s_lshl_b32 s16, s2, 3
	s_add_i32 s16, s16, s17
	s_waitcnt lgkmcnt(0)
	global_load_dwordx4 v[4:7], v2, s[8:9]
	global_load_dwordx4 v[8:11], v2, s[8:9] offset:16
	global_load_dwordx4 v[12:15], v2, s[10:11]
	global_load_dwordx4 v[16:19], v2, s[10:11] offset:16
	s_add_u32 s8, s6, 0xa3ce100
	s_addc_u32 s9, s7, 0
	s_add_u32 s28, s6, 0x9bc0000
	s_addc_u32 s29, s7, 0
	s_mov_b32 s10, 0xf0f0f0f0
	s_mov_b32 s11, 0xf0f0f0f0
	s_mov_b32 s12, 0xcccccccc
	s_mov_b32 s13, 0xcccccccc
	v_mov_b32_e32 v20, -1.0
	v_mov_b32_e32 v21, 1.0
	v_cndmask_b32_e64 v20, v20, v21, s[12:13]
	s_waitcnt vmcnt(0)
	s_mov_b32 s17, 0
.Ldprep_loop:
	s_mov_b32 s14, s16
	s_min_i32 s6, s16, 0x40ff
	s_lshl_b32 s7, s6, 11
	v_add_u32_e32 v22, s7, v1
	s_sub_i32 s6, s6, 0x100
	s_max_i32 s6, s6, 0
	s_lshr_b32 s7, s6, 6
	s_lshl_b32 s7, s7, 7
	s_and_b32 s6, s6, 63
	s_lshl_b32 s6, s6, 7
	v_mov_b32_e32 v28, s7
	v_mov_b32_e32 v29, s6
	v_cndmask_b32_e64 v23, v28, v29, s[10:11]
	v_add_u32_e32 v23, v23, v3
	s_add_i32 s16, s16, 0x800
	global_load_dwordx4 v[32:35], v22, s[8:9]
	global_load_dwordx4 v[36:39], v22, s[8:9] offset:1024
	global_load_dwordx4 v[40:43], v23, s[28:29] offset:0
	global_load_dwordx4 v[44:47], v23, s[28:29] offset:16
	global_load_dwordx4 v[48:51], v23, s[28:29] offset:32
	global_load_dwordx4 v[52:55], v23, s[28:29] offset:48
	s_mov_b32 s15, s16
	s_min_i32 s6, s16, 0x40ff
	s_lshl_b32 s7, s6, 11
	v_add_u32_e32 v24, s7, v1
	s_sub_i32 s6, s6, 0x100
	s_max_i32 s6, s6, 0
	s_lshr_b32 s7, s6, 6
	s_lshl_b32 s7, s7, 7
	s_and_b32 s6, s6, 63
	s_lshl_b32 s6, s6, 7
	v_mov_b32_e32 v28, s7
	v_mov_b32_e32 v29, s6
	v_cndmask_b32_e64 v25, v28, v29, s[10:11]
	v_add_u32_e32 v25, v25, v3
	s_add_i32 s16, s16, 0x800
	global_load_dwordx4 v[56:59], v24, s[8:9]
	global_load_dwordx4 v[60:63], v24, s[8:9] offset:1024
	global_load_dwordx4 v[64:67], v25, s[28:29] offset:0
	global_load_dwordx4 v[68:71], v25, s[28:29] offset:16
	global_load_dwordx4 v[72:75], v25, s[28:29] offset:32
	global_load_dwordx4 v[76:79], v25, s[28:29] offset:48
	s_mov_b32 s18, s16
	s_min_i32 s6, s16, 0x40ff
	s_lshl_b32 s7, s6, 11
	v_add_u32_e32 v26, s7, v1
	s_sub_i32 s6, s6, 0x100
	s_max_i32 s6, s6, 0
	s_lshr_b32 s7, s6, 6
	s_lshl_b32 s7, s7, 7
	s_and_b32 s6, s6, 63
	s_lshl_b32 s6, s6, 7
	v_mov_b32_e32 v28, s7
	v_mov_b32_e32 v29, s6
	v_cndmask_b32_e64 v27, v28, v29, s[10:11]
	v_add_u32_e32 v27, v27, v3
	s_add_i32 s16, s16, 0x800
	global_load_dwordx4 v[80:83], v26, s[8:9]
	global_load_dwordx4 v[84:87], v26, s[8:9] offset:1024
	global_load_dwordx4 v[88:91], v27, s[28:29] offset:0
	global_load_dwordx4 v[92:95], v27, s[28:29] offset:16
	global_load_dwordx4 v[96:99], v27, s[28:29] offset:32
	global_load_dwordx4 v[100:103], v27, s[28:29] offset:48
	s_waitcnt vmcnt(12)
	v_mul_f32_e32 v41, v41, v20
	v_mul_f32_e32 v43, v43, v20
	v_mul_f32_e32 v45, v45, v20
	v_mul_f32_e32 v47, v47, v20
	v_mul_f32_e32 v49, v49, v20
	v_mul_f32_e32 v51, v51, v20
	v_mul_f32_e32 v53, v53, v20
	v_mul_f32_e32 v55, v55, v20
	v_lshlrev_b32_e32 v104, 16, v32
	v_and_b32_e32 v105, 0xffff0000, v32
	v_lshlrev_b32_e32 v106, 16, v33
	v_and_b32_e32 v107, 0xffff0000, v33
	v_lshlrev_b32_e32 v108, 16, v34
	v_and_b32_e32 v109, 0xffff0000, v34
	v_lshlrev_b32_e32 v110, 16, v35
	v_and_b32_e32 v111, 0xffff0000, v35
	v_mul_f32_e32 v112, v104, v104
	v_fmac_f32_e32 v112, v105, v105
	v_fmac_f32_e32 v112, v106, v106
	v_fmac_f32_e32 v112, v107, v107
	v_fmac_f32_e32 v112, v108, v108
	v_fmac_f32_e32 v112, v109, v109
	v_fmac_f32_e32 v112, v110, v110
	v_fmac_f32_e32 v112, v111, v111
	s_nop 1
	v_add_f32_dpp v112, v112, v112 quad_perm:[1,0,3,2] row_mask:0xf bank_mask:0xf bound_ctrl:1
	s_nop 1
	v_add_f32_dpp v112, v112, v112 quad_perm:[2,3,0,1] row_mask:0xf bank_mask:0xf bound_ctrl:1
	s_nop 1
	v_add_f32_dpp v112, v112, v112 row_half_mirror row_mask:0xf bank_mask:0xf bound_ctrl:1
	v_mov_b32_e32 v113, 0x358637bd
	v_fmac_f32_e32 v113, 0x3c800000, v112
	v_rsq_f32_e32 v113, v113
	s_nop 0
	v_mul_f32_e32 v104, v104, v113
	v_mul_f32_e32 v104, v104, v4
	v_mul_f32_e32 v105, v105, v113
	v_mul_f32_e32 v105, v105, v5
	v_mul_f32_e32 v106, v106, v113
	v_mul_f32_e32 v106, v106, v6
	v_mul_f32_e32 v107, v107, v113
	v_mul_f32_e32 v107, v107, v7
	v_mul_f32_e32 v108, v108, v113
	v_mul_f32_e32 v108, v108, v8
	v_mul_f32_e32 v109, v109, v113
	v_mul_f32_e32 v109, v109, v9
	v_mul_f32_e32 v110, v110, v113
	v_mul_f32_e32 v110, v110, v10
	v_mul_f32_e32 v111, v111, v113
	v_mul_f32_e32 v111, v111, v11
	s_cmp_lt_u32 s14, 0x100
	s_cbranch_scc1 .Ldprep_norope_0_0
	v_mov_b32_dpp v114, v104 quad_perm:[2,3,0,1] row_mask:0xf bank_mask:0xf
	v_mov_b32_dpp v115, v105 quad_perm:[2,3,0,1] row_mask:0xf bank_mask:0xf
	v_mov_b32_dpp v116, v106 quad_perm:[2,3,0,1] row_mask:0xf bank_mask:0xf
	v_mov_b32_dpp v117, v107 quad_perm:[2,3,0,1] row_mask:0xf bank_mask:0xf
	v_mov_b32_dpp v118, v108 quad_perm:[2,3,0,1] row_mask:0xf bank_mask:0xf
	v_mov_b32_dpp v119, v109 quad_perm:[2,3,0,1] row_mask:0xf bank_mask:0xf
	v_mov_b32_dpp v120, v110 quad_perm:[2,3,0,1] row_mask:0xf bank_mask:0xf
	v_mov_b32_dpp v121, v111 quad_perm:[2,3,0,1] row_mask:0xf bank_mask:0xf
	v_mul_f32_e32 v122, v104, v40
	v_mul_f32_e32 v123, v105, v42
	v_mul_f32_e32 v124, v106, v44
	v_mul_f32_e32 v125, v107, v46
	v_mul_f32_e32 v126, v108, v48
	v_mul_f32_e32 v127, v109, v50
	v_mul_f32_e32 v128, v110, v52
	v_mul_f32_e32 v129, v111, v54
	v_fma_f32 v104, v114, v41, v122
	v_fma_f32 v105, v115, v43, v123
	v_fma_f32 v106, v116, v45, v124
	v_fma_f32 v107, v117, v47, v125
	v_fma_f32 v108, v118, v49, v126
	v_fma_f32 v109, v119, v51, v127
	v_fma_f32 v110, v120, v53, v128
	v_fma_f32 v111, v121, v55, v129
; __device__ __forceinline__ int tid_() { int t = threadIdx.x; asm volatile("" : "+v"(t)); return t; }
; __device__ __forceinline__ float bf2f(bf16_t b) { return __uint_as_float(((unsigned)b) << 16); }
; __device__ __forceinline__ bf16_t f2bf(float f) { return (bf16_t)(cvt_pk_bf16(f, 0.f) & 0xffffu); }
; __device__ __forceinline__ float rope_lane(float x, int lane, int t, const float* __restrict__ ROPE) {
;   const int ax = lane >> 5, i = lane & 15, pos = ax ? (t & 63) : (t >> 6);
;   const float cs = ROPE[pos * 32 + i * 2], sn = ROPE[pos * 32 + i * 2 + 1];
;   const float pr = __shfl_xor(x, 16, 64);
;   return (lane & 16) ? (x * cs + pr * sn) : (x * cs - pr * sn);
; }
; __device__ __forceinline__ void diff_prep(bf16_t* __restrict__ DQK, const float* __restrict__ wq, const float* __restrict__ wk, const float* __restrict__ ROPE) {
;   const int tid = tid_(); const int wid = tid >> 6, lane = tid & 63; const float w_q = wq[lane], w_k = wk[lane];
;   const int stride = gridDim.x * 8;
;   for (int r0 = blockIdx.x * 8 + wid; r0 < T_TOK; r0 += 2 * stride) {
;     const int r1 = r0 + stride; const bool has1 = r1 < T_TOK;
;     bf16_t* p0 = DQK + (size_t)r0 * 1024; bf16_t* p1 = DQK + (size_t)(has1 ? r1 : r0) * 1024;
;     float x0[16], x1[16];
; #pragma unroll
;     for (int g = 0; g < 16; ++g) { x0[g] = bf2f(p0[g * 64 + lane]); x1[g] = bf2f(p1[g * 64 + lane]); }
; #pragma unroll
;     for (int g = 0; g < 16; ++g) {
;       const float s0 = wave_sum(x0[g] * x0[g]), s1 = wave_sum(x1[g] * x1[g]);
;       float y0 = x0[g] * rsqrtf(s0 * (1.f / 64.f) + EPSN) * (g < 8 ? w_q : w_k), y1 = x1[g] * rsqrtf(s1 * (1.f / 64.f) + EPSN) * (g < 8 ? w_q : w_k);
;       if (r0 >= NCTX) y0 = rope_lane(y0, lane, r0 - NCTX, ROPE);
;       if (r1 >= NCTX) y1 = rope_lane(y1, lane, r1 - NCTX, ROPE);
;       p0[g * 64 + lane] = f2bf(y0); if (has1) p1[g * 64 + lane] = f2bf(y1);
;     }
;   }
; }
.Ldprep_norope_0_0:
	v_cvt_pk_bf16_f32 v130, v104, v105
	v_cvt_pk_bf16_f32 v131, v106, v107
	v_cvt_pk_bf16_f32 v132, v108, v109
	v_cvt_pk_bf16_f32 v133, v110, v111
	s_cmp_lt_u32 s14, 0x4100
	s_cbranch_scc0 .Ldprep_nostore_0_0
	global_store_dwordx4 v22, v[130:133], s[8:9]
.Ldprep_nostore_0_0:
	s_nop 1
	v_lshlrev_b32_e32 v104, 16, v36
	v_and_b32_e32 v105, 0xffff0000, v36
	v_lshlrev_b32_e32 v106, 16, v37
	v_and_b32_e32 v107, 0xffff0000, v37
	v_lshlrev_b32_e32 v108, 16, v38
	v_and_b32_e32 v109, 0xffff0000, v38
	v_lshlrev_b32_e32 v110, 16, v39
	v_and_b32_e32 v111, 0xffff0000, v39
	v_mul_f32_e32 v112, v104, v104
	v_fmac_f32_e32 v112, v105, v105
	v_fmac_f32_e32 v112, v106, v106
	v_fmac_f32_e32 v112, v107, v107
	v_fmac_f32_e32 v112, v108, v108
	v_fmac_f32_e32 v112, v109, v109
	v_fmac_f32_e32 v112, v110, v110
	v_fmac_f32_e32 v112, v111, v111
	s_nop 1
	v_add_f32_dpp v112, v112, v112 quad_perm:[1,0,3,2] row_mask:0xf bank_mask:0xf bound_ctrl:1
	s_nop 1
	v_add_f32_dpp v112, v112, v112 quad_perm:[2,3,0,1] row_mask:0xf bank_mask:0xf bound_ctrl:1
	s_nop 1
	v_add_f32_dpp v112, v112, v112 row_half_mirror row_mask:0xf bank_mask:0xf bound_ctrl:1
	v_mov_b32_e32 v113, 0x358637bd
	v_fmac_f32_e32 v113, 0x3c800000, v112
	v_rsq_f32_e32 v113, v113
	s_nop 0
	v_mul_f32_e32 v104, v104, v113
	v_mul_f32_e32 v104, v104, v12
	v_mul_f32_e32 v105, v105, v113
	v_mul_f32_e32 v105, v105, v13
	v_mul_f32_e32 v106, v106, v113
	v_mul_f32_e32 v106, v106, v14
	v_mul_f32_e32 v107, v107, v113
	v_mul_f32_e32 v107, v107, v15
	v_mul_f32_e32 v108, v108, v113
	v_mul_f32_e32 v108, v108, v16
	v_mul_f32_e32 v109, v109, v113
	v_mul_f32_e32 v109, v109, v17
	v_mul_f32_e32 v110, v110, v113
	v_mul_f32_e32 v110, v110, v18
	v_mul_f32_e32 v111, v111, v113
	v_mul_f32_e32 v111, v111, v19
	s_cmp_lt_u32 s14, 0x100
	s_cbranch_scc1 .Ldprep_norope_0_1
	v_mov_b32_dpp v114, v104 quad_perm:[2,3,0,1] row_mask:0xf bank_mask:0xf
	v_mov_b32_dpp v115, v105 quad_perm:[2,3,0,1] row_mask:0xf bank_mask:0xf
	v_mov_b32_dpp v116, v106 quad_perm:[2,3,0,1] row_mask:0xf bank_mask:0xf
	v_mov_b32_dpp v117, v107 quad_perm:[2,3,0,1] row_mask:0xf bank_mask:0xf
	v_mov_b32_dpp v118, v108 quad_perm:[2,3,0,1] row_mask:0xf bank_mask:0xf
	v_mov_b32_dpp v119, v109 quad_perm:[2,3,0,1] row_mask:0xf bank_mask:0xf
	v_mov_b32_dpp v120, v110 quad_perm:[2,3,0,1] row_mask:0xf bank_mask:0xf
	v_mov_b32_dpp v121, v111 quad_perm:[2,3,0,1] row_mask:0xf bank_mask:0xf
	v_mul_f32_e32 v122, v104, v40
	v_mul_f32_e32 v123, v105, v42
	v_mul_f32_e32 v124, v106, v44
	v_mul_f32_e32 v125, v107, v46
	v_mul_f32_e32 v126, v108, v48
	v_mul_f32_e32 v127, v109, v50
	v_mul_f32_e32 v128, v110, v52
	v_mul_f32_e32 v129, v111, v54
	v_fma_f32 v104, v114, v41, v122
	v_fma_f32 v105, v115, v43, v123
	v_fma_f32 v106, v116, v45, v124
	v_fma_f32 v107, v117, v47, v125
	v_fma_f32 v108, v118, v49, v126
	v_fma_f32 v109, v119, v51, v127
	v_fma_f32 v110, v120, v53, v128
	v_fma_f32 v111, v121, v55, v129
.Ldprep_norope_0_1:
	v_cvt_pk_bf16_f32 v130, v104, v105
	v_cvt_pk_bf16_f32 v131, v106, v107
	v_cvt_pk_bf16_f32 v132, v108, v109
	v_cvt_pk_bf16_f32 v133, v110, v111
	s_cmp_lt_u32 s14, 0x4100
	s_cbranch_scc0 .Ldprep_nostore_0_1
	global_store_dwordx4 v22, v[130:133], s[8:9] offset:1024
.Ldprep_nostore_0_1:
	s_nop 1
	s_waitcnt vmcnt(6)
	v_mul_f32_e32 v65, v65, v20
	v_mul_f32_e32 v67, v67, v20
	v_mul_f32_e32 v69, v69, v20
	v_mul_f32_e32 v71, v71, v20
	v_mul_f32_e32 v73, v73, v20
	v_mul_f32_e32 v75, v75, v20
	v_mul_f32_e32 v77, v77, v20
	v_mul_f32_e32 v79, v79, v20
	v_lshlrev_b32_e32 v104, 16, v56
	v_and_b32_e32 v105, 0xffff0000, v56
	v_lshlrev_b32_e32 v106, 16, v57
	v_and_b32_e32 v107, 0xffff0000, v57
	v_lshlrev_b32_e32 v108, 16, v58
	v_and_b32_e32 v109, 0xffff0000, v58
	v_lshlrev_b32_e32 v110, 16, v59
	v_and_b32_e32 v111, 0xffff0000, v59
	v_mul_f32_e32 v112, v104, v104
	v_fmac_f32_e32 v112, v105, v105
	v_fmac_f32_e32 v112, v106, v106
	v_fmac_f32_e32 v112, v107, v107
	v_fmac_f32_e32 v112, v108, v108
	v_fmac_f32_e32 v112, v109, v109
	v_fmac_f32_e32 v112, v110, v110
	v_fmac_f32_e32 v112, v111, v111
	s_nop 1
	v_add_f32_dpp v112, v112, v112 quad_perm:[1,0,3,2] row_mask:0xf bank_mask:0xf bound_ctrl:1
	s_nop 1
	v_add_f32_dpp v112, v112, v112 quad_perm:[2,3,0,1] row_mask:0xf bank_mask:0xf bound_ctrl:1
	s_nop 1
	v_add_f32_dpp v112, v112, v112 row_half_mirror row_mask:0xf bank_mask:0xf bound_ctrl:1
	v_mov_b32_e32 v113, 0x358637bd
	v_fmac_f32_e32 v113, 0x3c800000, v112
	v_rsq_f32_e32 v113, v113
	s_nop 0
	v_mul_f32_e32 v104, v104, v113
	v_mul_f32_e32 v104, v104, v4
	v_mul_f32_e32 v105, v105, v113
	v_mul_f32_e32 v105, v105, v5
	v_mul_f32_e32 v106, v106, v113
	v_mul_f32_e32 v106, v106, v6
	v_mul_f32_e32 v107, v107, v113
	v_mul_f32_e32 v107, v107, v7
	v_mul_f32_e32 v108, v108, v113
	v_mul_f32_e32 v108, v108, v8
	v_mul_f32_e32 v109, v109, v113
	v_mul_f32_e32 v109, v109, v9
	v_mul_f32_e32 v110, v110, v113
	v_mul_f32_e32 v110, v110, v10
	v_mul_f32_e32 v111, v111, v113
	v_mul_f32_e32 v111, v111, v11
	s_cmp_lt_u32 s15, 0x100
	s_cbranch_scc1 .Ldprep_norope_1_0
	v_mov_b32_dpp v114, v104 quad_perm:[2,3,0,1] row_mask:0xf bank_mask:0xf
	v_mov_b32_dpp v115, v105 quad_perm:[2,3,0,1] row_mask:0xf bank_mask:0xf
	v_mov_b32_dpp v116, v106 quad_perm:[2,3,0,1] row_mask:0xf bank_mask:0xf
	v_mov_b32_dpp v117, v107 quad_perm:[2,3,0,1] row_mask:0xf bank_mask:0xf
	v_mov_b32_dpp v118, v108 quad_perm:[2,3,0,1] row_mask:0xf bank_mask:0xf
	v_mov_b32_dpp v119, v109 quad_perm:[2,3,0,1] row_mask:0xf bank_mask:0xf
	v_mov_b32_dpp v120, v110 quad_perm:[2,3,0,1] row_mask:0xf bank_mask:0xf
	v_mov_b32_dpp v121, v111 quad_perm:[2,3,0,1] row_mask:0xf bank_mask:0xf
	v_mul_f32_e32 v122, v104, v64
	v_mul_f32_e32 v123, v105, v66
	v_mul_f32_e32 v124, v106, v68
	v_mul_f32_e32 v125, v107, v70
	v_mul_f32_e32 v126, v108, v72
	v_mul_f32_e32 v127, v109, v74
	v_mul_f32_e32 v128, v110, v76
	v_mul_f32_e32 v129, v111, v78
	v_fma_f32 v104, v114, v65, v122
	v_fma_f32 v105, v115, v67, v123
	v_fma_f32 v106, v116, v69, v124
	v_fma_f32 v107, v117, v71, v125
	v_fma_f32 v108, v118, v73, v126
	v_fma_f32 v109, v119, v75, v127
	v_fma_f32 v110, v120, v77, v128
	v_fma_f32 v111, v121, v79, v129
; __device__ __forceinline__ int tid_() { int t = threadIdx.x; asm volatile("" : "+v"(t)); return t; }
; __device__ __forceinline__ float bf2f(bf16_t b) { return __uint_as_float(((unsigned)b) << 16); }
; __device__ __forceinline__ bf16_t f2bf(float f) { return (bf16_t)(cvt_pk_bf16(f, 0.f) & 0xffffu); }
; __device__ __forceinline__ float rope_lane(float x, int lane, int t, const float* __restrict__ ROPE) {
;   const int ax = lane >> 5, i = lane & 15, pos = ax ? (t & 63) : (t >> 6);
;   const float cs = ROPE[pos * 32 + i * 2], sn = ROPE[pos * 32 + i * 2 + 1];
;   const float pr = __shfl_xor(x, 16, 64);
;   return (lane & 16) ? (x * cs + pr * sn) : (x * cs - pr * sn);
; }
; __device__ __forceinline__ void diff_prep(bf16_t* __restrict__ DQK, const float* __restrict__ wq, const float* __restrict__ wk, const float* __restrict__ ROPE) {
;   const int tid = tid_(); const int wid = tid >> 6, lane = tid & 63; const float w_q = wq[lane], w_k = wk[lane];
;   const int stride = gridDim.x * 8;
;   for (int r0 = blockIdx.x * 8 + wid; r0 < T_TOK; r0 += 2 * stride) {
;     const int r1 = r0 + stride; const bool has1 = r1 < T_TOK;
;     bf16_t* p0 = DQK + (size_t)r0 * 1024; bf16_t* p1 = DQK + (size_t)(has1 ? r1 : r0) * 1024;
;     float x0[16], x1[16];
; #pragma unroll
;     for (int g = 0; g < 16; ++g) { x0[g] = bf2f(p0[g * 64 + lane]); x1[g] = bf2f(p1[g * 64 + lane]); }
; #pragma unroll
;     for (int g = 0; g < 16; ++g) {
;       const float s0 = wave_sum(x0[g] * x0[g]), s1 = wave_sum(x1[g] * x1[g]);
;       float y0 = x0[g] * rsqrtf(s0 * (1.f / 64.f) + EPSN) * (g < 8 ? w_q : w_k), y1 = x1[g] * rsqrtf(s1 * (1.f / 64.f) + EPSN) * (g < 8 ? w_q : w_k);
;       if (r0 >= NCTX) y0 = rope_lane(y0, lane, r0 - NCTX, ROPE);
;       if (r1 >= NCTX) y1 = rope_lane(y1, lane, r1 - NCTX, ROPE);
;       p0[g * 64 + lane] = f2bf(y0); if (has1) p1[g * 64 + lane] = f2bf(y1);
;     }
;   }
; }
.Ldprep_norope_1_0:
	v_cvt_pk_bf16_f32 v130, v104, v105
	v_cvt_pk_bf16_f32 v131, v106, v107
	v_cvt_pk_bf16_f32 v132, v108, v109
	v_cvt_pk_bf16_f32 v133, v110, v111
	s_cmp_lt_u32 s15, 0x4100
	s_cbranch_scc0 .Ldprep_nostore_1_0
	global_store_dwordx4 v24, v[130:133], s[8:9]
.Ldprep_nostore_1_0:
	s_nop 1
	v_lshlrev_b32_e32 v104, 16, v60
	v_and_b32_e32 v105, 0xffff0000, v60
	v_lshlrev_b32_e32 v106, 16, v61
	v_and_b32_e32 v107, 0xffff0000, v61
	v_lshlrev_b32_e32 v108, 16, v62
	v_and_b32_e32 v109, 0xffff0000, v62
	v_lshlrev_b32_e32 v110, 16, v63
	v_and_b32_e32 v111, 0xffff0000, v63
	v_mul_f32_e32 v112, v104, v104
	v_fmac_f32_e32 v112, v105, v105
	v_fmac_f32_e32 v112, v106, v106
	v_fmac_f32_e32 v112, v107, v107
	v_fmac_f32_e32 v112, v108, v108
	v_fmac_f32_e32 v112, v109, v109
	v_fmac_f32_e32 v112, v110, v110
	v_fmac_f32_e32 v112, v111, v111
	s_nop 1
	v_add_f32_dpp v112, v112, v112 quad_perm:[1,0,3,2] row_mask:0xf bank_mask:0xf bound_ctrl:1
	s_nop 1
	v_add_f32_dpp v112, v112, v112 quad_perm:[2,3,0,1] row_mask:0xf bank_mask:0xf bound_ctrl:1
	s_nop 1
	v_add_f32_dpp v112, v112, v112 row_half_mirror row_mask:0xf bank_mask:0xf bound_ctrl:1
	v_mov_b32_e32 v113, 0x358637bd
	v_fmac_f32_e32 v113, 0x3c800000, v112
	v_rsq_f32_e32 v113, v113
	s_nop 0
	v_mul_f32_e32 v104, v104, v113
	v_mul_f32_e32 v104, v104, v12
	v_mul_f32_e32 v105, v105, v113
	v_mul_f32_e32 v105, v105, v13
	v_mul_f32_e32 v106, v106, v113
	v_mul_f32_e32 v106, v106, v14
	v_mul_f32_e32 v107, v107, v113
	v_mul_f32_e32 v107, v107, v15
	v_mul_f32_e32 v108, v108, v113
	v_mul_f32_e32 v108, v108, v16
	v_mul_f32_e32 v109, v109, v113
	v_mul_f32_e32 v109, v109, v17
	v_mul_f32_e32 v110, v110, v113
	v_mul_f32_e32 v110, v110, v18
	v_mul_f32_e32 v111, v111, v113
	v_mul_f32_e32 v111, v111, v19
	s_cmp_lt_u32 s15, 0x100
	s_cbranch_scc1 .Ldprep_norope_1_1
	v_mov_b32_dpp v114, v104 quad_perm:[2,3,0,1] row_mask:0xf bank_mask:0xf
	v_mov_b32_dpp v115, v105 quad_perm:[2,3,0,1] row_mask:0xf bank_mask:0xf
	v_mov_b32_dpp v116, v106 quad_perm:[2,3,0,1] row_mask:0xf bank_mask:0xf
	v_mov_b32_dpp v117, v107 quad_perm:[2,3,0,1] row_mask:0xf bank_mask:0xf
	v_mov_b32_dpp v118, v108 quad_perm:[2,3,0,1] row_mask:0xf bank_mask:0xf
	v_mov_b32_dpp v119, v109 quad_perm:[2,3,0,1] row_mask:0xf bank_mask:0xf
	v_mov_b32_dpp v120, v110 quad_perm:[2,3,0,1] row_mask:0xf bank_mask:0xf
	v_mov_b32_dpp v121, v111 quad_perm:[2,3,0,1] row_mask:0xf bank_mask:0xf
	v_mul_f32_e32 v122, v104, v64
	v_mul_f32_e32 v123, v105, v66
	v_mul_f32_e32 v124, v106, v68
	v_mul_f32_e32 v125, v107, v70
	v_mul_f32_e32 v126, v108, v72
	v_mul_f32_e32 v127, v109, v74
	v_mul_f32_e32 v128, v110, v76
	v_mul_f32_e32 v129, v111, v78
	v_fma_f32 v104, v114, v65, v122
	v_fma_f32 v105, v115, v67, v123
	v_fma_f32 v106, v116, v69, v124
	v_fma_f32 v107, v117, v71, v125
	v_fma_f32 v108, v118, v73, v126
	v_fma_f32 v109, v119, v75, v127
	v_fma_f32 v110, v120, v77, v128
	v_fma_f32 v111, v121, v79, v129
.Ldprep_norope_1_1:
	v_cvt_pk_bf16_f32 v130, v104, v105
	v_cvt_pk_bf16_f32 v131, v106, v107
	v_cvt_pk_bf16_f32 v132, v108, v109
	v_cvt_pk_bf16_f32 v133, v110, v111
	s_cmp_lt_u32 s15, 0x4100
	s_cbranch_scc0 .Ldprep_nostore_1_1
	global_store_dwordx4 v24, v[130:133], s[8:9] offset:1024
.Ldprep_nostore_1_1:
	s_nop 1
	s_waitcnt vmcnt(0)
	v_mul_f32_e32 v89, v89, v20
	v_mul_f32_e32 v91, v91, v20
	v_mul_f32_e32 v93, v93, v20
	v_mul_f32_e32 v95, v95, v20
	v_mul_f32_e32 v97, v97, v20
	v_mul_f32_e32 v99, v99, v20
	v_mul_f32_e32 v101, v101, v20
	v_mul_f32_e32 v103, v103, v20
	v_lshlrev_b32_e32 v104, 16, v80
	v_and_b32_e32 v105, 0xffff0000, v80
	v_lshlrev_b32_e32 v106, 16, v81
	v_and_b32_e32 v107, 0xffff0000, v81
	v_lshlrev_b32_e32 v108, 16, v82
	v_and_b32_e32 v109, 0xffff0000, v82
	v_lshlrev_b32_e32 v110, 16, v83
	v_and_b32_e32 v111, 0xffff0000, v83
	v_mul_f32_e32 v112, v104, v104
	v_fmac_f32_e32 v112, v105, v105
	v_fmac_f32_e32 v112, v106, v106
	v_fmac_f32_e32 v112, v107, v107
	v_fmac_f32_e32 v112, v108, v108
	v_fmac_f32_e32 v112, v109, v109
	v_fmac_f32_e32 v112, v110, v110
	v_fmac_f32_e32 v112, v111, v111
	s_nop 1
	v_add_f32_dpp v112, v112, v112 quad_perm:[1,0,3,2] row_mask:0xf bank_mask:0xf bound_ctrl:1
	s_nop 1
	v_add_f32_dpp v112, v112, v112 quad_perm:[2,3,0,1] row_mask:0xf bank_mask:0xf bound_ctrl:1
	s_nop 1
	v_add_f32_dpp v112, v112, v112 row_half_mirror row_mask:0xf bank_mask:0xf bound_ctrl:1
	v_mov_b32_e32 v113, 0x358637bd
	v_fmac_f32_e32 v113, 0x3c800000, v112
	v_rsq_f32_e32 v113, v113
	s_nop 0
	v_mul_f32_e32 v104, v104, v113
	v_mul_f32_e32 v104, v104, v4
	v_mul_f32_e32 v105, v105, v113
	v_mul_f32_e32 v105, v105, v5
	v_mul_f32_e32 v106, v106, v113
	v_mul_f32_e32 v106, v106, v6
	v_mul_f32_e32 v107, v107, v113
	v_mul_f32_e32 v107, v107, v7
	v_mul_f32_e32 v108, v108, v113
	v_mul_f32_e32 v108, v108, v8
	v_mul_f32_e32 v109, v109, v113
	v_mul_f32_e32 v109, v109, v9
	v_mul_f32_e32 v110, v110, v113
	v_mul_f32_e32 v110, v110, v10
	v_mul_f32_e32 v111, v111, v113
	v_mul_f32_e32 v111, v111, v11
	s_cmp_lt_u32 s18, 0x100
	s_cbranch_scc1 .Ldprep_norope_2_0
	v_mov_b32_dpp v114, v104 quad_perm:[2,3,0,1] row_mask:0xf bank_mask:0xf
	v_mov_b32_dpp v115, v105 quad_perm:[2,3,0,1] row_mask:0xf bank_mask:0xf
	v_mov_b32_dpp v116, v106 quad_perm:[2,3,0,1] row_mask:0xf bank_mask:0xf
	v_mov_b32_dpp v117, v107 quad_perm:[2,3,0,1] row_mask:0xf bank_mask:0xf
	v_mov_b32_dpp v118, v108 quad_perm:[2,3,0,1] row_mask:0xf bank_mask:0xf
	v_mov_b32_dpp v119, v109 quad_perm:[2,3,0,1] row_mask:0xf bank_mask:0xf
	v_mov_b32_dpp v120, v110 quad_perm:[2,3,0,1] row_mask:0xf bank_mask:0xf
	v_mov_b32_dpp v121, v111 quad_perm:[2,3,0,1] row_mask:0xf bank_mask:0xf
	v_mul_f32_e32 v122, v104, v88
	v_mul_f32_e32 v123, v105, v90
	v_mul_f32_e32 v124, v106, v92
	v_mul_f32_e32 v125, v107, v94
	v_mul_f32_e32 v126, v108, v96
	v_mul_f32_e32 v127, v109, v98
	v_mul_f32_e32 v128, v110, v100
	v_mul_f32_e32 v129, v111, v102
	v_fma_f32 v104, v114, v89, v122
	v_fma_f32 v105, v115, v91, v123
	v_fma_f32 v106, v116, v93, v124
	v_fma_f32 v107, v117, v95, v125
	v_fma_f32 v108, v118, v97, v126
	v_fma_f32 v109, v119, v99, v127
	v_fma_f32 v110, v120, v101, v128
	v_fma_f32 v111, v121, v103, v129
; __device__ __forceinline__ int tid_() { int t = threadIdx.x; asm volatile("" : "+v"(t)); return t; }
; __device__ __forceinline__ float bf2f(bf16_t b) { return __uint_as_float(((unsigned)b) << 16); }
; __device__ __forceinline__ bf16_t f2bf(float f) { return (bf16_t)(cvt_pk_bf16(f, 0.f) & 0xffffu); }
; __device__ __forceinline__ void diff_prep(bf16_t* __restrict__ DQK, const float* __restrict__ wq, const float* __restrict__ wk, const float* __restrict__ ROPE) {
;   const int tid = tid_(); const int wid = tid >> 6, lane = tid & 63; const float w_q = wq[lane], w_k = wk[lane];
;   const int stride = gridDim.x * 8;
;   for (int r0 = blockIdx.x * 8 + wid; r0 < T_TOK; r0 += 2 * stride) {
;     const int r1 = r0 + stride; const bool has1 = r1 < T_TOK;
;     bf16_t* p0 = DQK + (size_t)r0 * 1024; bf16_t* p1 = DQK + (size_t)(has1 ? r1 : r0) * 1024;
;     float x0[16], x1[16];
; #pragma unroll
;     for (int g = 0; g < 16; ++g) { x0[g] = bf2f(p0[g * 64 + lane]); x1[g] = bf2f(p1[g * 64 + lane]); }
; #pragma unroll
;     for (int g = 0; g < 16; ++g) {
;       const float s0 = wave_sum(x0[g] * x0[g]), s1 = wave_sum(x1[g] * x1[g]);
;       float y0 = x0[g] * rsqrtf(s0 * (1.f / 64.f) + EPSN) * (g < 8 ? w_q : w_k), y1 = x1[g] * rsqrtf(s1 * (1.f / 64.f) + EPSN) * (g < 8 ? w_q : w_k);
;       if (r0 >= NCTX) y0 = rope_lane(y0, lane, r0 - NCTX, ROPE);
;       if (r1 >= NCTX) y1 = rope_lane(y1, lane, r1 - NCTX, ROPE);
;       p0[g * 64 + lane] = f2bf(y0); if (has1) p1[g * 64 + lane] = f2bf(y1);
;     }
;   }
; }
.Ldprep_norope_2_0:
	v_cvt_pk_bf16_f32 v130, v104, v105
	v_cvt_pk_bf16_f32 v131, v106, v107
	v_cvt_pk_bf16_f32 v132, v108, v109
	v_cvt_pk_bf16_f32 v133, v110, v111
	s_cmp_lt_u32 s18, 0x4100
	s_cbranch_scc0 .Ldprep_nostore_2_0
	global_store_dwordx4 v26, v[130:133], s[8:9]
.Ldprep_nostore_2_0:
	s_nop 1
	v_lshlrev_b32_e32 v104, 16, v84
	v_and_b32_e32 v105, 0xffff0000, v84
	v_lshlrev_b32_e32 v106, 16, v85
	v_and_b32_e32 v107, 0xffff0000, v85
	v_lshlrev_b32_e32 v108, 16, v86
	v_and_b32_e32 v109, 0xffff0000, v86
	v_lshlrev_b32_e32 v110, 16, v87
	v_and_b32_e32 v111, 0xffff0000, v87
	v_mul_f32_e32 v112, v104, v104
	v_fmac_f32_e32 v112, v105, v105
	v_fmac_f32_e32 v112, v106, v106
	v_fmac_f32_e32 v112, v107, v107
	v_fmac_f32_e32 v112, v108, v108
	v_fmac_f32_e32 v112, v109, v109
	v_fmac_f32_e32 v112, v110, v110
	v_fmac_f32_e32 v112, v111, v111
	s_nop 1
	v_add_f32_dpp v112, v112, v112 quad_perm:[1,0,3,2] row_mask:0xf bank_mask:0xf bound_ctrl:1
	s_nop 1
	v_add_f32_dpp v112, v112, v112 quad_perm:[2,3,0,1] row_mask:0xf bank_mask:0xf bound_ctrl:1
	s_nop 1
	v_add_f32_dpp v112, v112, v112 row_half_mirror row_mask:0xf bank_mask:0xf bound_ctrl:1
	v_mov_b32_e32 v113, 0x358637bd
	v_fmac_f32_e32 v113, 0x3c800000, v112
	v_rsq_f32_e32 v113, v113
	s_nop 0
	v_mul_f32_e32 v104, v104, v113
	v_mul_f32_e32 v104, v104, v12
	v_mul_f32_e32 v105, v105, v113
	v_mul_f32_e32 v105, v105, v13
	v_mul_f32_e32 v106, v106, v113
	v_mul_f32_e32 v106, v106, v14
	v_mul_f32_e32 v107, v107, v113
	v_mul_f32_e32 v107, v107, v15
	v_mul_f32_e32 v108, v108, v113
	v_mul_f32_e32 v108, v108, v16
	v_mul_f32_e32 v109, v109, v113
	v_mul_f32_e32 v109, v109, v17
	v_mul_f32_e32 v110, v110, v113
	v_mul_f32_e32 v110, v110, v18
	v_mul_f32_e32 v111, v111, v113
	v_mul_f32_e32 v111, v111, v19
	s_cmp_lt_u32 s18, 0x100
	s_cbranch_scc1 .Ldprep_norope_2_1
	v_mov_b32_dpp v114, v104 quad_perm:[2,3,0,1] row_mask:0xf bank_mask:0xf
	v_mov_b32_dpp v115, v105 quad_perm:[2,3,0,1] row_mask:0xf bank_mask:0xf
	v_mov_b32_dpp v116, v106 quad_perm:[2,3,0,1] row_mask:0xf bank_mask:0xf
	v_mov_b32_dpp v117, v107 quad_perm:[2,3,0,1] row_mask:0xf bank_mask:0xf
	v_mov_b32_dpp v118, v108 quad_perm:[2,3,0,1] row_mask:0xf bank_mask:0xf
	v_mov_b32_dpp v119, v109 quad_perm:[2,3,0,1] row_mask:0xf bank_mask:0xf
	v_mov_b32_dpp v120, v110 quad_perm:[2,3,0,1] row_mask:0xf bank_mask:0xf
	v_mov_b32_dpp v121, v111 quad_perm:[2,3,0,1] row_mask:0xf bank_mask:0xf
	v_mul_f32_e32 v122, v104, v88
	v_mul_f32_e32 v123, v105, v90
	v_mul_f32_e32 v124, v106, v92
	v_mul_f32_e32 v125, v107, v94
	v_mul_f32_e32 v126, v108, v96
	v_mul_f32_e32 v127, v109, v98
	v_mul_f32_e32 v128, v110, v100
	v_mul_f32_e32 v129, v111, v102
	v_fma_f32 v104, v114, v89, v122
	v_fma_f32 v105, v115, v91, v123
	v_fma_f32 v106, v116, v93, v124
	v_fma_f32 v107, v117, v95, v125
	v_fma_f32 v108, v118, v97, v126
	v_fma_f32 v109, v119, v99, v127
	v_fma_f32 v110, v120, v101, v128
	v_fma_f32 v111, v121, v103, v129
.Ldprep_norope_2_1:
	v_cvt_pk_bf16_f32 v130, v104, v105
	v_cvt_pk_bf16_f32 v131, v106, v107
	v_cvt_pk_bf16_f32 v132, v108, v109
	v_cvt_pk_bf16_f32 v133, v110, v111
	s_cmp_lt_u32 s18, 0x4100
	s_cbranch_scc0 .Ldprep_nostore_2_1
	global_store_dwordx4 v26, v[130:133], s[8:9] offset:1024
.Ldprep_nostore_2_1:
	s_nop 1
	s_add_i32 s17, s17, 1
	s_cmp_lt_u32 s17, 3
	s_cbranch_scc1 .Ldprep_loop
	s_mov_b64 s[22:23], exec

; __device__ __forceinline__ void mla_prep(const bf16_t* __restrict__ U, const bf16_t* __restrict__ CQ, bf16_t* __restrict__ Qa, bf16_t* __restrict__ Ka, bf16_t* __restrict__ Va, ...
;   const int tid = tid_(); const int wid = tid >> 6, lane = tid & 63;
;   const float wq0 = qkq[lane], wq1 = qkq[64 + lane], wq2 = qkq[128 + lane], wk0 = qkk[lane], wk1 = qkk[64 + lane], wk2 = qkk[128 + lane];
;   auto do_row = [&](const int r) {
;     const bf16_t* cq = CQ + (size_t)r * 768; float sq = 0.f, skv = 0.f;
; #pragma unroll
;     for (int i = 0; i < 6; ++i) { const float x = bf2f(cq[i * 64 + lane]); sq += x * x; }
; #pragma unroll
;     for (int i = 0; i < 4; ++i) { const float x = bf2f(cq[384 + i * 64 + lane]); skv += x * x; }
;     sq = wave_sum(sq); skv = wave_sum(skv);
;     const float rq = rsqrtf(sq * (1.f / 384.f) + EPSN), rkv = rsqrtf(skv * (1.f / 256.f) + EPSN);
;     const float kr = bf2f(cq[640 + lane]);
;     const bool lat = r >= NCTX; const int t = r - NCTX;
;     const bf16_t* u = U + (size_t)r * 1792;
; #pragma unroll
;     for (int h = 0; h < 4; ++h) {
;       float q0 = bf2f(u[h * 192 + lane]) * rq, q1 = bf2f(u[h * 192 + 64 + lane]) * rq, q2 = bf2f(u[h * 192 + 128 + lane]) * rq;
;       float ss = wave_sum(q0 * q0 + q1 * q1 + q2 * q2); float rs = rsqrtf(ss * (1.f / 192.f) + EPSN);
;       q0 = q0 * rs * wq0; q1 = q1 * rs * wq1; q2 = q2 * rs * wq2; if (lat) q2 = rope_lane(q2, lane, t, ROPE);
;       bf16_t* qo = Qa + (size_t)r * 768 + h * 192; qo[lane] = f2bf(q0); qo[64 + lane] = f2bf(q1); qo[128 + lane] = f2bf(q2);
;       const bf16_t* kv = u + 768 + h * 256;
;       float k0 = bf2f(kv[lane]) * rkv, k1 = bf2f(kv[64 + lane]) * rkv; const float v0 = bf2f(kv[128 + lane]) * rkv, v1 = bf2f(kv[192 + lane]) * rkv;
;       ss = wave_sum(k0 * k0 + k1 * k1 + kr * kr); rs = rsqrtf(ss * (1.f / 192.f) + EPSN);
;       k0 = k0 * rs * wk0; k1 = k1 * rs * wk1; float k2 = kr * rs * wk2; if (lat) k2 = rope_lane(k2, lane, t, ROPE);
;       bf16_t* ko = Ka + (size_t)r * 768 + h * 192; ko[lane] = f2bf(k0); ko[64 + lane] = f2bf(k1); ko[128 + lane] = f2bf(k2);
;       bf16_t* vo = Va + (size_t)r * 512 + h * 128; vo[lane] = f2bf(v0); vo[64 + lane] = f2bf(v1);
;     }
;     };
;   const int stride = gridDim.x * 8;
;   for (int r = blockIdx.x * 8 + wid; r < T_TOK; r += 2 * stride) { do_row(r); if (r + stride < T_TOK) do_row(r + stride); }
; }
.LBB0_2422:
	s_or_b64 exec, exec, s[4:5]
	s_add_u32 s4, s24, 0xdcae100
	s_addc_u32 s5, s25, 0
	v_readlane_b32 s18, v255, 42
	v_readlane_b32 s19, v255, 43
	s_add_u32 s26, s18, 0xf50e100
	s_mov_b64 s[10:11], s[0:1]
	s_mov_b64 s[8:9], s[0:1]
	s_mov_b64 s[6:7], s[0:1]
	v_mov_b32_e32 v1, v187
	s_addc_u32 s27, s19, 0
	v_readlane_b32 s20, v255, 44
	s_waitcnt lgkmcnt(0)
	s_barrier
	v_readlane_b32 s14, v254, 12
	v_ashrrev_i32_e32 v0, 6, v1
	v_readlane_b32 s21, v255, 45
	s_add_u32 s48, s20, 0x10d6e100
	v_add_u32_e32 v0, s14, v0
	s_addc_u32 s49, s21, 0
	v_cmp_gt_i32_e32 vcc, s86, v0
	s_and_saveexec_b64 s[14:15], vcc
	s_cbranch_execz .LBB0_2459
	s_mulk_i32 s34, 0xc0
	s_movk_i32 s64, 0x600
	s_load_dwordx2 s[6:7], s[0:1], 0xd8
	s_load_dwordx2 s[8:9], s[0:1], 0x88
	s_load_dwordx2 s[10:11], s[0:1], 0x90
	v_and_b32_e32 v0, 63, v187
	v_lshlrev_b32_e32 v1, 4, v0
	v_and_b32_e32 v2, 1, v0
	v_lshlrev_b32_e32 v2, 6, v2
	s_lshl_b32 s12, s34, 2
	v_and_b32_e32 v40, 31, v0
	v_min_u32_e32 v40, 23, v40
	v_lshlrev_b32_e32 v41, 5, v40
	v_add_u32_e32 v41, s12, v41
	v_and_b32_e32 v42, 15, v0
	v_lshlrev_b32_e32 v43, 5, v42
	v_add_u32_e32 v43, s12, v43
	v_and_b32_e32 v44, 7, v0
	v_lshlrev_b32_e32 v45, 5, v44
	v_add_u32_e32 v45, s12, v45
	v_add_u32_e32 v45, 0x200, v45
	v_readfirstlane_b32 s17, v187
	s_nop 3
	s_lshr_b32 s17, s17, 6
	s_lshl_b32 s16, s2, 3
	s_add_i32 s16, s16, s17
	s_waitcnt lgkmcnt(0)
	global_load_dwordx4 v[4:7], v41, s[8:9]
	global_load_dwordx4 v[8:11], v41, s[8:9] offset:16
	global_load_dwordx4 v[12:15], v43, s[10:11]
	global_load_dwordx4 v[16:19], v43, s[10:11] offset:16
	global_load_dwordx4 v[20:23], v45, s[10:11]
	global_load_dwordx4 v[24:27], v45, s[10:11] offset:16
	v_lshlrev_b32_e32 v28, 4, v42
	v_add_u32_e32 v28, 0x400, v28
	v_lshlrev_b32_e32 v29, 4, v44
	v_add_u32_e32 v29, 0x500, v29
	v_lshrrev_b32_e32 v46, 5, v0
	v_mul_u32_u24_e32 v30, 0x180, v46
	v_lshl_add_u32 v30, v40, 4, v30
	v_add_u32_e32 v31, 0x600, v1
	v_and_b32_e32 v47, 31, v0
	v_mul_u32_u24_e32 v37, 0x180, v46
	v_lshl_add_u32 v37, v47, 4, v37
	v_lshrrev_b32_e32 v47, 3, v0
	v_mul_u32_u24_e32 v38, 0x180, v47
	v_lshl_add_u32 v38, v44, 4, v38
	v_add_u32_e32 v38, 0x100, v38
	v_mul_u32_u24_e32 v32, 0x180, v46
	v_lshl_add_u32 v32, v42, 4, v32
	v_lshlrev_b32_e32 v33, 8, v46
	v_lshl_add_u32 v33, v42, 4, v33
	v_and_b32_e32 v47, 16, v0
	v_cmp_eq_u32_e32 vcc, 0, v47
	s_nop 3
	s_mov_b64 s[18:19], vcc
	v_and_b32_e32 v47, 2, v0
	v_cmp_ne_u32_e32 vcc, 0, v47
	v_mov_b32_e32 v3, -1.0
	v_mov_b32_e32 v48, 1.0
	s_nop 0
	v_cndmask_b32_e32 v3, v3, v48, vcc
	s_add_u32 s20, s6, 0xa3ce100
	s_addc_u32 s21, s7, 0
	s_add_u32 s8, s6, 0x125ce100
	s_addc_u32 s9, s7, 0
	s_add_u32 s10, s6, 0x9bc0000
	s_addc_u32 s11, s7, 0
	s_mov_b32 s6, s20
	s_mov_b32 s7, s21
	s_waitcnt vmcnt(0)
	s_mov_b32 s17, 0
.Lmprep_loop:
	s_mov_b32 s12, s16
	s_min_i32 s22, s16, 0x40ff
	s_mul_i32 s23, s22, 0x600
	v_add_u32_e32 v50, s23, v1
	v_add_u32_e32 v51, s23, v28
	v_add_u32_e32 v52, s23, v29
	s_mul_i32 s23, s22, 0xe00
	v_add_u32_e32 v53, s23, v30
	v_add_u32_e32 v166, s23, v31
	s_sub_i32 s22, s22, 0x100
	s_max_i32 s22, s22, 0
	s_lshr_b32 s23, s22, 6
	s_lshl_b32 s23, s23, 7
	s_and_b32 s22, s22, 63
	s_lshl_b32 s22, s22, 7
	v_and_b32_e32 v49, 4, v0
	v_cmp_ne_u32_e32 vcc, 0, v49
	v_mov_b32_e32 v48, s23
	v_mov_b32_e32 v49, s22
	v_cndmask_b32_e32 v167, v48, v49, vcc
	v_add_u32_e32 v167, v167, v2
	s_add_i32 s16, s16, 0x800
	global_load_dwordx4 v[64:67], v50, s[8:9]
	global_load_dwordx4 v[68:71], v51, s[8:9]
	global_load_dwordx4 v[72:75], v52, s[8:9]
	global_load_dwordx4 v[76:79], v53, s[6:7]
	global_load_dwordx4 v[80:83], v53, s[6:7] offset:768
	global_load_dwordx4 v[84:87], v166, s[6:7]
	global_load_dwordx4 v[88:91], v166, s[6:7] offset:1024
	global_load_dwordx4 v[92:95], v167, s[10:11] offset:0
	global_load_dwordx4 v[96:99], v167, s[10:11] offset:16
	global_load_dwordx4 v[100:103], v167, s[10:11] offset:32
	global_load_dwordx4 v[104:107], v167, s[10:11] offset:48
	s_mov_b32 s13, s16
	s_min_i32 s22, s16, 0x40ff
	s_mul_i32 s23, s22, 0x600
	v_add_u32_e32 v154, s23, v1
	v_add_u32_e32 v155, s23, v28
	v_add_u32_e32 v156, s23, v29
	s_mul_i32 s23, s22, 0xe00
	v_add_u32_e32 v157, s23, v30
	v_add_u32_e32 v168, s23, v31
	s_sub_i32 s22, s22, 0x100
	s_max_i32 s22, s22, 0
	s_lshr_b32 s23, s22, 6
	s_lshl_b32 s23, s23, 7
	s_and_b32 s22, s22, 63
	s_lshl_b32 s22, s22, 7
	v_and_b32_e32 v49, 4, v0
	v_cmp_ne_u32_e32 vcc, 0, v49
	v_mov_b32_e32 v48, s23
	v_mov_b32_e32 v49, s22
	v_cndmask_b32_e32 v169, v48, v49, vcc
	v_add_u32_e32 v169, v169, v2
	s_add_i32 s16, s16, 0x800
	global_load_dwordx4 v[108:111], v154, s[8:9]
	global_load_dwordx4 v[112:115], v155, s[8:9]
	global_load_dwordx4 v[116:119], v156, s[8:9]
	global_load_dwordx4 v[120:123], v157, s[6:7]
	global_load_dwordx4 v[124:127], v157, s[6:7] offset:768
	global_load_dwordx4 v[128:131], v168, s[6:7]
	global_load_dwordx4 v[132:135], v168, s[6:7] offset:1024
	global_load_dwordx4 v[136:139], v169, s[10:11] offset:0
	global_load_dwordx4 v[140:143], v169, s[10:11] offset:16
	global_load_dwordx4 v[146:149], v169, s[10:11] offset:32
	global_load_dwordx4 v[150:153], v169, s[10:11] offset:48
	s_waitcnt vmcnt(11)
; __device__ __forceinline__ float bf2f(bf16_t b) { return __uint_as_float(((unsigned)b) << 16); }
; __device__ __forceinline__ void mla_prep(const bf16_t* __restrict__ U, const bf16_t* __restrict__ CQ, bf16_t* __restrict__ Qa, bf16_t* __restrict__ Ka, bf16_t* __restrict__ Va, ...
;     ...
;     const bf16_t* cq = CQ + (size_t)r * 768; float sq = 0.f, skv = 0.f;
; #pragma unroll
;     for (int i = 0; i < 6; ++i) { const float x = bf2f(cq[i * 64 + lane]); sq += x * x; }
; #pragma unroll
;     for (int i = 0; i < 4; ++i) { const float x = bf2f(cq[384 + i * 64 + lane]); skv += x * x; }
;     sq = wave_sum(sq); skv = wave_sum(skv);
;     const float rq = rsqrtf(sq * (1.f / 384.f) + EPSN), rkv = rsqrtf(skv * (1.f / 256.f) + EPSN);
;     const float kr = bf2f(cq[640 + lane]);
;     const bool lat = r >= NCTX; const int t = r - NCTX;
;     const bf16_t* u = U + (size_t)r * 1792;
; #pragma unroll
;     for (int h = 0; h < 4; ++h) {
;       float q0 = bf2f(u[h * 192 + lane]) * rq, q1 = bf2f(u[h * 192 + 64 + lane]) * rq, q2 = bf2f(u[h * 192 + 128 + lane]) * rq;
;       float ss = wave_sum(q0 * q0 + q1 * q1 + q2 * q2); float rs = rsqrtf(ss * (1.f / 192.f) + EPSN);
;       q0 = q0 * rs * wq0; q1 = q1 * rs * wq1; q2 = q2 * rs * wq2; if (lat) q2 = rope_lane(q2, lane, t, ROPE);
	v_lshlrev_b32_e32 v170, 16, v64
	v_and_b32_e32 v171, 0xffff0000, v64
	v_lshlrev_b32_e32 v172, 16, v65
	v_and_b32_e32 v173, 0xffff0000, v65
	v_lshlrev_b32_e32 v174, 16, v66
	v_and_b32_e32 v175, 0xffff0000, v66
	v_lshlrev_b32_e32 v176, 16, v67
	v_and_b32_e32 v177, 0xffff0000, v67
	v_mul_f32_e32 v178, v170, v170
	v_fmac_f32_e32 v178, v171, v171
	v_fmac_f32_e32 v178, v172, v172
	v_fmac_f32_e32 v178, v173, v173
	v_fmac_f32_e32 v178, v174, v174
	v_fmac_f32_e32 v178, v175, v175
	v_fmac_f32_e32 v178, v176, v176
	v_fmac_f32_e32 v178, v177, v177
	v_lshlrev_b32_e32 v170, 16, v68
	v_and_b32_e32 v171, 0xffff0000, v68
	v_lshlrev_b32_e32 v172, 16, v69
	v_and_b32_e32 v173, 0xffff0000, v69
	v_lshlrev_b32_e32 v174, 16, v70
	v_and_b32_e32 v175, 0xffff0000, v70
	v_lshlrev_b32_e32 v176, 16, v71
	v_and_b32_e32 v177, 0xffff0000, v71
	v_mul_f32_e32 v179, v170, v170
	v_fmac_f32_e32 v179, v171, v171
	v_fmac_f32_e32 v179, v172, v172
	v_fmac_f32_e32 v179, v173, v173
	v_fmac_f32_e32 v179, v174, v174
	v_fmac_f32_e32 v179, v175, v175
	v_fmac_f32_e32 v179, v176, v176
	v_fmac_f32_e32 v179, v177, v177
	v_lshlrev_b32_e32 v214, 16, v72
	v_and_b32_e32 v215, 0xffff0000, v72
	v_lshlrev_b32_e32 v216, 16, v73
	v_and_b32_e32 v217, 0xffff0000, v73
	v_lshlrev_b32_e32 v218, 16, v74
	v_and_b32_e32 v219, 0xffff0000, v74
	v_lshlrev_b32_e32 v220, 16, v75
	v_and_b32_e32 v221, 0xffff0000, v75
	v_mul_f32_e32 v180, v214, v214
	v_fmac_f32_e32 v180, v215, v215
	v_fmac_f32_e32 v180, v216, v216
	v_fmac_f32_e32 v180, v217, v217
	v_fmac_f32_e32 v180, v218, v218
	v_fmac_f32_e32 v180, v219, v219
	v_fmac_f32_e32 v180, v220, v220
	v_fmac_f32_e32 v180, v221, v221
	v_cmp_gt_u32_e32 vcc, 48, v0
	s_nop 1
	v_cndmask_b32_e32 v181, 0, v178, vcc
	v_cndmask_b32_e32 v178, v178, v144, vcc
	v_cmp_gt_u32_e32 vcc, 16, v0
	s_nop 1
	v_cndmask_b32_e32 v179, 0, v179, vcc
	v_add_f32_e32 v178, v178, v179
	s_nop 1
	v_add_f32_dpp v181, v181, v181 quad_perm:[1,0,3,2] row_mask:0xf bank_mask:0xf bound_ctrl:1
	s_nop 1
	v_add_f32_dpp v181, v181, v181 quad_perm:[2,3,0,1] row_mask:0xf bank_mask:0xf bound_ctrl:1
	s_nop 1
	v_add_f32_dpp v181, v181, v181 row_ror:4 row_mask:0xf bank_mask:0xf bound_ctrl:1
	s_nop 1
	v_add_f32_dpp v181, v181, v181 row_ror:8 row_mask:0xf bank_mask:0xf bound_ctrl:1
	v_mov_b32_e32 v251, v181
	s_nop 1
	v_permlane16_swap_b32_e32 v181, v251
	v_add_f32_e32 v181, v181, v251
	v_mov_b32_e32 v251, v181
	s_nop 1
	v_permlane32_swap_b32_e32 v181, v251
	v_add_f32_e32 v181, v181, v251
	s_nop 1
	v_add_f32_dpp v178, v178, v178 quad_perm:[1,0,3,2] row_mask:0xf bank_mask:0xf bound_ctrl:1
	s_nop 1
	v_add_f32_dpp v178, v178, v178 quad_perm:[2,3,0,1] row_mask:0xf bank_mask:0xf bound_ctrl:1
	s_nop 1
	v_add_f32_dpp v178, v178, v178 row_ror:4 row_mask:0xf bank_mask:0xf bound_ctrl:1
	s_nop 1
	v_add_f32_dpp v178, v178, v178 row_ror:8 row_mask:0xf bank_mask:0xf bound_ctrl:1
	v_mov_b32_e32 v251, v178
	s_nop 1
	v_permlane16_swap_b32_e32 v178, v251
	v_add_f32_e32 v178, v178, v251
	v_mov_b32_e32 v251, v178
	s_nop 1
	v_permlane32_swap_b32_e32 v178, v251
	v_add_f32_e32 v178, v178, v251
	s_nop 1
	v_add_f32_dpp v180, v180, v180 quad_perm:[1,0,3,2] row_mask:0xf bank_mask:0xf bound_ctrl:1
	s_nop 1
	v_add_f32_dpp v180, v180, v180 quad_perm:[2,3,0,1] row_mask:0xf bank_mask:0xf bound_ctrl:1
	s_nop 1
	v_add_f32_dpp v180, v180, v180 row_half_mirror row_mask:0xf bank_mask:0xf bound_ctrl:1
	v_mov_b32_e32 v182, 0x358637bd
	v_fmac_f32_e32 v182, 0x3b2aaaab, v181
	v_rsq_f32_e32 v182, v182
	s_nop 0
	v_mov_b32_e32 v183, 0x358637bd
	v_fmac_f32_e32 v183, 0x3b800000, v178
	v_rsq_f32_e32 v183, v183
	s_nop 0
	v_mov_b32_e32 v184, v180
	v_mul_f32_e32 v93, v93, v3
	v_mul_f32_e32 v95, v95, v3
	v_mul_f32_e32 v97, v97, v3
	v_mul_f32_e32 v99, v99, v3
	v_mul_f32_e32 v101, v101, v3
	v_mul_f32_e32 v103, v103, v3
	v_mul_f32_e32 v105, v105, v3
	v_mul_f32_e32 v107, v107, v3
	v_lshlrev_b32_e32 v170, 16, v76
	v_and_b32_e32 v171, 0xffff0000, v76
	v_lshlrev_b32_e32 v172, 16, v77
	v_and_b32_e32 v173, 0xffff0000, v77
	v_lshlrev_b32_e32 v174, 16, v78
	v_and_b32_e32 v175, 0xffff0000, v78
	v_lshlrev_b32_e32 v176, 16, v79
	v_and_b32_e32 v177, 0xffff0000, v79
	v_mul_f32_e32 v170, v170, v182
	v_mul_f32_e32 v171, v171, v182
	v_mul_f32_e32 v172, v172, v182
	v_mul_f32_e32 v173, v173, v182
	v_mul_f32_e32 v174, v174, v182
	v_mul_f32_e32 v175, v175, v182
	v_mul_f32_e32 v176, v176, v182
	v_mul_f32_e32 v177, v177, v182
	v_mul_f32_e32 v181, v170, v170
	v_fmac_f32_e32 v181, v171, v171
	v_fmac_f32_e32 v181, v172, v172
	v_fmac_f32_e32 v181, v173, v173
	v_fmac_f32_e32 v181, v174, v174
	v_fmac_f32_e32 v181, v175, v175
	v_fmac_f32_e32 v181, v176, v176
	v_fmac_f32_e32 v181, v177, v177
	v_and_b32_e32 v251, 31, v0
	v_cmp_gt_u32_e32 vcc, 24, v251
	s_nop 1
	v_cndmask_b32_e32 v181, 0, v181, vcc
	s_nop 1
	v_add_f32_dpp v181, v181, v181 quad_perm:[1,0,3,2] row_mask:0xf bank_mask:0xf bound_ctrl:1
	s_nop 1
	v_add_f32_dpp v181, v181, v181 quad_perm:[2,3,0,1] row_mask:0xf bank_mask:0xf bound_ctrl:1
	s_nop 1
	v_add_f32_dpp v181, v181, v181 row_ror:4 row_mask:0xf bank_mask:0xf bound_ctrl:1
	s_nop 1
	v_add_f32_dpp v181, v181, v181 row_ror:8 row_mask:0xf bank_mask:0xf bound_ctrl:1
	v_mov_b32_e32 v251, v181
	s_nop 1
	v_permlane16_swap_b32_e32 v181, v251
	v_add_f32_e32 v181, v181, v251
	v_mov_b32_e32 v185, 0x358637bd
	v_fmac_f32_e32 v185, 0x3baaaaab, v181
	v_rsq_f32_e32 v185, v185
	s_nop 0
	v_mul_f32_e32 v170, v170, v185
	v_mul_f32_e32 v170, v170, v4
	v_mul_f32_e32 v171, v171, v185
	v_mul_f32_e32 v171, v171, v5
	v_mul_f32_e32 v172, v172, v185
	v_mul_f32_e32 v172, v172, v6
	v_mul_f32_e32 v173, v173, v185
	v_mul_f32_e32 v173, v173, v7
	v_mul_f32_e32 v174, v174, v185
	v_mul_f32_e32 v174, v174, v8
	v_mul_f32_e32 v175, v175, v185
	v_mul_f32_e32 v175, v175, v9
	v_mul_f32_e32 v176, v176, v185
	v_mul_f32_e32 v176, v176, v10
	v_mul_f32_e32 v177, v177, v185
	v_mul_f32_e32 v177, v177, v11
	s_cmp_lt_u32 s12, 0x100
	s_cbranch_scc1 .Lmprep_qnr_0_0
; __device__ __forceinline__ float bf2f(bf16_t b) { return __uint_as_float(((unsigned)b) << 16); }
; __device__ __forceinline__ bf16_t f2bf(float f) { return (bf16_t)(cvt_pk_bf16(f, 0.f) & 0xffffu); }
; __device__ __forceinline__ void mla_prep(const bf16_t* __restrict__ U, const bf16_t* __restrict__ CQ, bf16_t* __restrict__ Qa, bf16_t* __restrict__ Ka, bf16_t* __restrict__ Va, ...
;     ...
;     for (int h = 0; h < 4; ++h) {
;       float q0 = bf2f(u[h * 192 + lane]) * rq, q1 = bf2f(u[h * 192 + 64 + lane]) * rq, q2 = bf2f(u[h * 192 + 128 + lane]) * rq;
;       float ss = wave_sum(q0 * q0 + q1 * q1 + q2 * q2); float rs = rsqrtf(ss * (1.f / 192.f) + EPSN);
;       q0 = q0 * rs * wq0; q1 = q1 * rs * wq1; q2 = q2 * rs * wq2; if (lat) q2 = rope_lane(q2, lane, t, ROPE);
;       bf16_t* qo = Qa + (size_t)r * 768 + h * 192; qo[lane] = f2bf(q0); qo[64 + lane] = f2bf(q1); qo[128 + lane] = f2bf(q2);
	v_mov_b32_dpp v222, v170 quad_perm:[2,3,0,1] row_mask:0xf bank_mask:0xf
	v_mov_b32_dpp v223, v171 quad_perm:[2,3,0,1] row_mask:0xf bank_mask:0xf
	v_mov_b32_dpp v224, v172 quad_perm:[2,3,0,1] row_mask:0xf bank_mask:0xf
	v_mov_b32_dpp v225, v173 quad_perm:[2,3,0,1] row_mask:0xf bank_mask:0xf
	v_mov_b32_dpp v226, v174 quad_perm:[2,3,0,1] row_mask:0xf bank_mask:0xf
	v_mov_b32_dpp v227, v175 quad_perm:[2,3,0,1] row_mask:0xf bank_mask:0xf
	v_mov_b32_dpp v228, v176 quad_perm:[2,3,0,1] row_mask:0xf bank_mask:0xf
	v_mov_b32_dpp v229, v177 quad_perm:[2,3,0,1] row_mask:0xf bank_mask:0xf
	v_mul_f32_e32 v230, v170, v92
	v_mul_f32_e32 v231, v171, v94
	v_mul_f32_e32 v232, v172, v96
	v_mul_f32_e32 v233, v173, v98
	v_mul_f32_e32 v234, v174, v100
	v_mul_f32_e32 v235, v175, v102
	v_mul_f32_e32 v236, v176, v104
	v_mul_f32_e32 v237, v177, v106
	v_fma_f32 v222, v222, v93, v230
	v_fma_f32 v223, v223, v95, v231
	v_fma_f32 v224, v224, v97, v232
	v_fma_f32 v225, v225, v99, v233
	v_fma_f32 v226, v226, v101, v234
	v_fma_f32 v227, v227, v103, v235
	v_fma_f32 v228, v228, v105, v236
	v_fma_f32 v229, v229, v107, v237
	v_and_b32_e32 v251, 24, v0
	v_cmp_eq_u32_e32 vcc, 16, v251
	s_nop 1
	v_cndmask_b32_e32 v170, v170, v222, vcc
	v_cndmask_b32_e32 v171, v171, v223, vcc
	v_cndmask_b32_e32 v172, v172, v224, vcc
	v_cndmask_b32_e32 v173, v173, v225, vcc
	v_cndmask_b32_e32 v174, v174, v226, vcc
	v_cndmask_b32_e32 v175, v175, v227, vcc
	v_cndmask_b32_e32 v176, v176, v228, vcc
	v_cndmask_b32_e32 v177, v177, v229, vcc
.Lmprep_qnr_0_0:
	v_cvt_pk_bf16_f32 v238, v170, v171
	v_cvt_pk_bf16_f32 v239, v172, v173
	v_cvt_pk_bf16_f32 v240, v174, v175
	v_cvt_pk_bf16_f32 v241, v176, v177
	s_cmp_lt_u32 s12, 0x4100
	s_cbranch_scc0 .Lmprep_qns_0_0
	s_mul_i32 s22, s12, 0x600
	v_add_u32_e32 v251, s22, v37
	s_mov_b32 exec_lo, 0x00ffffff
	s_mov_b32 exec_hi, 0x00ffffff
	global_store_dwordx4 v251, v[238:241], s[4:5]
	s_mov_b64 exec, -1
.Lmprep_qns_0_0:
	s_nop 1
	v_lshlrev_b32_e32 v170, 16, v80
	v_and_b32_e32 v171, 0xffff0000, v80
	v_lshlrev_b32_e32 v172, 16, v81
	v_and_b32_e32 v173, 0xffff0000, v81
	v_lshlrev_b32_e32 v174, 16, v82
	v_and_b32_e32 v175, 0xffff0000, v82
	v_lshlrev_b32_e32 v176, 16, v83
	v_and_b32_e32 v177, 0xffff0000, v83
	v_mul_f32_e32 v170, v170, v182
	v_mul_f32_e32 v171, v171, v182
	v_mul_f32_e32 v172, v172, v182
	v_mul_f32_e32 v173, v173, v182
	v_mul_f32_e32 v174, v174, v182
	v_mul_f32_e32 v175, v175, v182
	v_mul_f32_e32 v176, v176, v182
	v_mul_f32_e32 v177, v177, v182
	v_mul_f32_e32 v181, v170, v170
	v_fmac_f32_e32 v181, v171, v171
	v_fmac_f32_e32 v181, v172, v172
	v_fmac_f32_e32 v181, v173, v173
	v_fmac_f32_e32 v181, v174, v174
	v_fmac_f32_e32 v181, v175, v175
	v_fmac_f32_e32 v181, v176, v176
	v_fmac_f32_e32 v181, v177, v177
	v_and_b32_e32 v251, 31, v0
	v_cmp_gt_u32_e32 vcc, 24, v251
	s_nop 1
	v_cndmask_b32_e32 v181, 0, v181, vcc
	s_nop 1
	v_add_f32_dpp v181, v181, v181 quad_perm:[1,0,3,2] row_mask:0xf bank_mask:0xf bound_ctrl:1
	s_nop 1
	v_add_f32_dpp v181, v181, v181 quad_perm:[2,3,0,1] row_mask:0xf bank_mask:0xf bound_ctrl:1
	s_nop 1
	v_add_f32_dpp v181, v181, v181 row_ror:4 row_mask:0xf bank_mask:0xf bound_ctrl:1
	s_nop 1
	v_add_f32_dpp v181, v181, v181 row_ror:8 row_mask:0xf bank_mask:0xf bound_ctrl:1
	v_mov_b32_e32 v251, v181
	s_nop 1
	v_permlane16_swap_b32_e32 v181, v251
	v_add_f32_e32 v181, v181, v251
	v_mov_b32_e32 v185, 0x358637bd
	v_fmac_f32_e32 v185, 0x3baaaaab, v181
	v_rsq_f32_e32 v185, v185
	s_nop 0
	v_mul_f32_e32 v170, v170, v185
	v_mul_f32_e32 v170, v170, v4
	v_mul_f32_e32 v171, v171, v185
	v_mul_f32_e32 v171, v171, v5
	v_mul_f32_e32 v172, v172, v185
	v_mul_f32_e32 v172, v172, v6
	v_mul_f32_e32 v173, v173, v185
	v_mul_f32_e32 v173, v173, v7
	v_mul_f32_e32 v174, v174, v185
	v_mul_f32_e32 v174, v174, v8
	v_mul_f32_e32 v175, v175, v185
	v_mul_f32_e32 v175, v175, v9
	v_mul_f32_e32 v176, v176, v185
	v_mul_f32_e32 v176, v176, v10
	v_mul_f32_e32 v177, v177, v185
	v_mul_f32_e32 v177, v177, v11
	s_cmp_lt_u32 s12, 0x100
	s_cbranch_scc1 .Lmprep_qnr_0_1
	v_mov_b32_dpp v222, v170 quad_perm:[2,3,0,1] row_mask:0xf bank_mask:0xf
	v_mov_b32_dpp v223, v171 quad_perm:[2,3,0,1] row_mask:0xf bank_mask:0xf
	v_mov_b32_dpp v224, v172 quad_perm:[2,3,0,1] row_mask:0xf bank_mask:0xf
	v_mov_b32_dpp v225, v173 quad_perm:[2,3,0,1] row_mask:0xf bank_mask:0xf
	v_mov_b32_dpp v226, v174 quad_perm:[2,3,0,1] row_mask:0xf bank_mask:0xf
	v_mov_b32_dpp v227, v175 quad_perm:[2,3,0,1] row_mask:0xf bank_mask:0xf
	v_mov_b32_dpp v228, v176 quad_perm:[2,3,0,1] row_mask:0xf bank_mask:0xf
	v_mov_b32_dpp v229, v177 quad_perm:[2,3,0,1] row_mask:0xf bank_mask:0xf
	v_mul_f32_e32 v230, v170, v92
	v_mul_f32_e32 v231, v171, v94
	v_mul_f32_e32 v232, v172, v96
	v_mul_f32_e32 v233, v173, v98
	v_mul_f32_e32 v234, v174, v100
	v_mul_f32_e32 v235, v175, v102
	v_mul_f32_e32 v236, v176, v104
	v_mul_f32_e32 v237, v177, v106
	v_fma_f32 v222, v222, v93, v230
	v_fma_f32 v223, v223, v95, v231
	v_fma_f32 v224, v224, v97, v232
	v_fma_f32 v225, v225, v99, v233
	v_fma_f32 v226, v226, v101, v234
	v_fma_f32 v227, v227, v103, v235
	v_fma_f32 v228, v228, v105, v236
	v_fma_f32 v229, v229, v107, v237
	v_and_b32_e32 v251, 24, v0
	v_cmp_eq_u32_e32 vcc, 16, v251
	s_nop 1
	v_cndmask_b32_e32 v170, v170, v222, vcc
	v_cndmask_b32_e32 v171, v171, v223, vcc
	v_cndmask_b32_e32 v172, v172, v224, vcc
	v_cndmask_b32_e32 v173, v173, v225, vcc
	v_cndmask_b32_e32 v174, v174, v226, vcc
	v_cndmask_b32_e32 v175, v175, v227, vcc
	v_cndmask_b32_e32 v176, v176, v228, vcc
	v_cndmask_b32_e32 v177, v177, v229, vcc
; __device__ __forceinline__ float bf2f(bf16_t b) { return __uint_as_float(((unsigned)b) << 16); }
; __device__ __forceinline__ bf16_t f2bf(float f) { return (bf16_t)(cvt_pk_bf16(f, 0.f) & 0xffffu); }
; __device__ __forceinline__ void mla_prep(const bf16_t* __restrict__ U, const bf16_t* __restrict__ CQ, bf16_t* __restrict__ Qa, bf16_t* __restrict__ Ka, bf16_t* __restrict__ Va, ...
;     ...
;       const bf16_t* kv = u + 768 + h * 256;
;       float k0 = bf2f(kv[lane]) * rkv, k1 = bf2f(kv[64 + lane]) * rkv; const float v0 = bf2f(kv[128 + lane]) * rkv, v1 = bf2f(kv[192 + lane]) * rkv;
;       ss = wave_sum(k0 * k0 + k1 * k1 + kr * kr); rs = rsqrtf(ss * (1.f / 192.f) + EPSN);
;       k0 = k0 * rs * wk0; k1 = k1 * rs * wk1; float k2 = kr * rs * wk2; if (lat) k2 = rope_lane(k2, lane, t, ROPE);
;       bf16_t* ko = Ka + (size_t)r * 768 + h * 192; ko[lane] = f2bf(k0); ko[64 + lane] = f2bf(k1); ko[128 + lane] = f2bf(k2);
;       bf16_t* vo = Va + (size_t)r * 512 + h * 128; vo[lane] = f2bf(v0); vo[64 + lane] = f2bf(v1);
.Lmprep_qnr_0_1:
	v_cvt_pk_bf16_f32 v238, v170, v171
	v_cvt_pk_bf16_f32 v239, v172, v173
	v_cvt_pk_bf16_f32 v240, v174, v175
	v_cvt_pk_bf16_f32 v241, v176, v177
	s_cmp_lt_u32 s12, 0x4100
	s_cbranch_scc0 .Lmprep_qns_0_1
	s_mul_i32 s22, s12, 0x600
	v_add_u32_e32 v251, s22, v37
	s_mov_b32 exec_lo, 0x00ffffff
	s_mov_b32 exec_hi, 0x00ffffff
	global_store_dwordx4 v251, v[238:241], s[4:5] offset:768
	s_mov_b64 exec, -1
.Lmprep_qns_0_1:
	s_nop 1
	v_lshlrev_b32_e32 v170, 16, v84
	v_and_b32_e32 v171, 0xffff0000, v84
	v_lshlrev_b32_e32 v172, 16, v85
	v_and_b32_e32 v173, 0xffff0000, v85
	v_lshlrev_b32_e32 v174, 16, v86
	v_and_b32_e32 v175, 0xffff0000, v86
	v_lshlrev_b32_e32 v176, 16, v87
	v_and_b32_e32 v177, 0xffff0000, v87
	v_mul_f32_e32 v170, v170, v183
	v_mul_f32_e32 v171, v171, v183
	v_mul_f32_e32 v172, v172, v183
	v_mul_f32_e32 v173, v173, v183
	v_mul_f32_e32 v174, v174, v183
	v_mul_f32_e32 v175, v175, v183
	v_mul_f32_e32 v176, v176, v183
	v_mul_f32_e32 v177, v177, v183
	v_mul_f32_e32 v181, v170, v170
	v_fmac_f32_e32 v181, v171, v171
	v_fmac_f32_e32 v181, v172, v172
	v_fmac_f32_e32 v181, v173, v173
	v_fmac_f32_e32 v181, v174, v174
	v_fmac_f32_e32 v181, v175, v175
	v_fmac_f32_e32 v181, v176, v176
	v_fmac_f32_e32 v181, v177, v177
	s_nop 1
	v_add_f32_dpp v181, v181, v181 quad_perm:[1,0,3,2] row_mask:0xf bank_mask:0xf bound_ctrl:1
	s_nop 1
	v_add_f32_dpp v181, v181, v181 quad_perm:[2,3,0,1] row_mask:0xf bank_mask:0xf bound_ctrl:1
	s_nop 1
	v_add_f32_dpp v181, v181, v181 row_ror:4 row_mask:0xf bank_mask:0xf bound_ctrl:1
	s_nop 1
	v_add_f32_dpp v181, v181, v181 row_ror:8 row_mask:0xf bank_mask:0xf bound_ctrl:1
	v_add_f32_e32 v181, v181, v184
	v_mov_b32_e32 v185, 0x358637bd
	v_fmac_f32_e32 v185, 0x3baaaaab, v181
	v_rsq_f32_e32 v185, v185
	s_nop 0
	v_readlane_b32 s20, v185, 0
	v_readlane_b32 s21, v185, 32
	v_lshrrev_b32_e32 v251, 3, v0
	s_nop 1
	v_mov_b32_e32 v250, s20
	v_mov_b32_e32 v230, s21
	v_cmp_eq_u32_e32 vcc, 1, v251
	s_nop 1
	v_cndmask_b32_e32 v250, v250, v230, vcc
	v_mul_f32_e32 v242, v170, v185
	v_mul_f32_e32 v242, v242, v12
	v_mul_f32_e32 v243, v171, v185
	v_mul_f32_e32 v243, v243, v13
	v_mul_f32_e32 v244, v172, v185
	v_mul_f32_e32 v244, v244, v14
	v_mul_f32_e32 v245, v173, v185
	v_mul_f32_e32 v245, v245, v15
	v_mul_f32_e32 v246, v174, v185
	v_mul_f32_e32 v246, v246, v16
	v_mul_f32_e32 v247, v175, v185
	v_mul_f32_e32 v247, v247, v17
	v_mul_f32_e32 v248, v176, v185
	v_mul_f32_e32 v248, v248, v18
	v_mul_f32_e32 v249, v177, v185
	v_mul_f32_e32 v249, v249, v19
	v_cndmask_b32_e64 v170, v170, v242, s[18:19]
	v_cndmask_b32_e64 v171, v171, v243, s[18:19]
	v_cndmask_b32_e64 v172, v172, v244, s[18:19]
	v_cndmask_b32_e64 v173, v173, v245, s[18:19]
	v_cndmask_b32_e64 v174, v174, v246, s[18:19]
	v_cndmask_b32_e64 v175, v175, v247, s[18:19]
	v_cndmask_b32_e64 v176, v176, v248, s[18:19]
	v_cndmask_b32_e64 v177, v177, v249, s[18:19]
	v_cvt_pk_bf16_f32 v238, v170, v171
	v_cvt_pk_bf16_f32 v239, v172, v173
	v_cvt_pk_bf16_f32 v240, v174, v175
	v_cvt_pk_bf16_f32 v241, v176, v177
	s_cmp_lt_u32 s12, 0x4100
	s_cbranch_scc0 .Lmprep_kvns_0_0
	s_mul_i32 s22, s12, 0x600
	v_add_u32_e32 v181, s22, v32
	s_lshl_b32 s22, s12, 10
	v_add_u32_e32 v251, s22, v33
	s_mov_b64 exec, s[18:19]
	global_store_dwordx4 v181, v[238:241], s[26:27]
	s_not_b64 exec, s[18:19]
	global_store_dwordx4 v251, v[238:241], s[48:49]
	s_mov_b64 exec, -1
.Lmprep_kvns_0_0:
	s_nop 1
	v_lshlrev_b32_e32 v170, 16, v88
	v_and_b32_e32 v171, 0xffff0000, v88
	v_lshlrev_b32_e32 v172, 16, v89
	v_and_b32_e32 v173, 0xffff0000, v89
	v_lshlrev_b32_e32 v174, 16, v90
	v_and_b32_e32 v175, 0xffff0000, v90
	v_lshlrev_b32_e32 v176, 16, v91
	v_and_b32_e32 v177, 0xffff0000, v91
	v_mul_f32_e32 v170, v170, v183
	v_mul_f32_e32 v171, v171, v183
	v_mul_f32_e32 v172, v172, v183
	v_mul_f32_e32 v173, v173, v183
	v_mul_f32_e32 v174, v174, v183
	v_mul_f32_e32 v175, v175, v183
	v_mul_f32_e32 v176, v176, v183
	v_mul_f32_e32 v177, v177, v183
	v_mul_f32_e32 v181, v170, v170
	v_fmac_f32_e32 v181, v171, v171
	v_fmac_f32_e32 v181, v172, v172
	v_fmac_f32_e32 v181, v173, v173
	v_fmac_f32_e32 v181, v174, v174
	v_fmac_f32_e32 v181, v175, v175
	v_fmac_f32_e32 v181, v176, v176
	v_fmac_f32_e32 v181, v177, v177
	s_nop 1
	v_add_f32_dpp v181, v181, v181 quad_perm:[1,0,3,2] row_mask:0xf bank_mask:0xf bound_ctrl:1
	s_nop 1
	v_add_f32_dpp v181, v181, v181 quad_perm:[2,3,0,1] row_mask:0xf bank_mask:0xf bound_ctrl:1
	s_nop 1
	v_add_f32_dpp v181, v181, v181 row_ror:4 row_mask:0xf bank_mask:0xf bound_ctrl:1
	s_nop 1
	v_add_f32_dpp v181, v181, v181 row_ror:8 row_mask:0xf bank_mask:0xf bound_ctrl:1
	v_add_f32_e32 v181, v181, v184
	v_mov_b32_e32 v185, 0x358637bd
	v_fmac_f32_e32 v185, 0x3baaaaab, v181
	v_rsq_f32_e32 v185, v185
	s_nop 0
	v_readlane_b32 s20, v185, 0
	v_readlane_b32 s21, v185, 32
	v_lshrrev_b32_e32 v251, 3, v0
	s_nop 1
	v_mov_b32_e32 v230, s20
	v_cmp_eq_u32_e32 vcc, 2, v251
	s_nop 1
	v_cndmask_b32_e32 v250, v250, v230, vcc
	v_mov_b32_e32 v230, s21
	v_cmp_eq_u32_e32 vcc, 3, v251
	s_nop 1
	v_cndmask_b32_e32 v250, v250, v230, vcc
	v_mul_f32_e32 v242, v170, v185
	v_mul_f32_e32 v242, v242, v12
	v_mul_f32_e32 v243, v171, v185
	v_mul_f32_e32 v243, v243, v13
	v_mul_f32_e32 v244, v172, v185
	v_mul_f32_e32 v244, v244, v14
	v_mul_f32_e32 v245, v173, v185
	v_mul_f32_e32 v245, v245, v15
	v_mul_f32_e32 v246, v174, v185
	v_mul_f32_e32 v246, v246, v16
	v_mul_f32_e32 v247, v175, v185
	v_mul_f32_e32 v247, v247, v17
	v_mul_f32_e32 v248, v176, v185
	v_mul_f32_e32 v248, v248, v18
	v_mul_f32_e32 v249, v177, v185
	v_mul_f32_e32 v249, v249, v19
	v_cndmask_b32_e64 v170, v170, v242, s[18:19]
	v_cndmask_b32_e64 v171, v171, v243, s[18:19]
	v_cndmask_b32_e64 v172, v172, v244, s[18:19]
	v_cndmask_b32_e64 v173, v173, v245, s[18:19]
	v_cndmask_b32_e64 v174, v174, v246, s[18:19]
	v_cndmask_b32_e64 v175, v175, v247, s[18:19]
	v_cndmask_b32_e64 v176, v176, v248, s[18:19]
	v_cndmask_b32_e64 v177, v177, v249, s[18:19]
	v_cvt_pk_bf16_f32 v238, v170, v171
	v_cvt_pk_bf16_f32 v239, v172, v173
	v_cvt_pk_bf16_f32 v240, v174, v175
	v_cvt_pk_bf16_f32 v241, v176, v177
	s_cmp_lt_u32 s12, 0x4100
	s_cbranch_scc0 .Lmprep_kvns_0_1
	s_mul_i32 s22, s12, 0x600
	v_add_u32_e32 v181, s22, v32
	s_lshl_b32 s22, s12, 10
	v_add_u32_e32 v251, s22, v33
	s_mov_b64 exec, s[18:19]
	global_store_dwordx4 v181, v[238:241], s[26:27] offset:768
	s_not_b64 exec, s[18:19]
	global_store_dwordx4 v251, v[238:241], s[48:49] offset:512
	s_mov_b64 exec, -1
; __device__ __forceinline__ float bf2f(bf16_t b) { return __uint_as_float(((unsigned)b) << 16); }
; __device__ __forceinline__ bf16_t f2bf(float f) { return (bf16_t)(cvt_pk_bf16(f, 0.f) & 0xffffu); }
; __device__ __forceinline__ void mla_prep(const bf16_t* __restrict__ U, const bf16_t* __restrict__ CQ, bf16_t* __restrict__ Qa, bf16_t* __restrict__ Ka, bf16_t* __restrict__ Va, ...
;     ...
;     const bf16_t* cq = CQ + (size_t)r * 768; float sq = 0.f, skv = 0.f;
; #pragma unroll
;     for (int i = 0; i < 6; ++i) { const float x = bf2f(cq[i * 64 + lane]); sq += x * x; }
; #pragma unroll
;     for (int i = 0; i < 4; ++i) { const float x = bf2f(cq[384 + i * 64 + lane]); skv += x * x; }
;     sq = wave_sum(sq); skv = wave_sum(skv);
;     const float rq = rsqrtf(sq * (1.f / 384.f) + EPSN), rkv = rsqrtf(skv * (1.f / 256.f) + EPSN);
;     const float kr = bf2f(cq[640 + lane]);
;     ...
;       float k0 = bf2f(kv[lane]) * rkv, k1 = bf2f(kv[64 + lane]) * rkv; const float v0 = bf2f(kv[128 + lane]) * rkv, v1 = bf2f(kv[192 + lane]) * rkv;
;       ss = wave_sum(k0 * k0 + k1 * k1 + kr * kr); rs = rsqrtf(ss * (1.f / 192.f) + EPSN);
;       k0 = k0 * rs * wk0; k1 = k1 * rs * wk1; float k2 = kr * rs * wk2; if (lat) k2 = rope_lane(k2, lane, t, ROPE);
;       bf16_t* ko = Ka + (size_t)r * 768 + h * 192; ko[lane] = f2bf(k0); ko[64 + lane] = f2bf(k1); ko[128 + lane] = f2bf(k2);
.Lmprep_kvns_0_1:
	s_nop 1
	v_mul_f32_e32 v170, v214, v250
	v_mul_f32_e32 v170, v170, v20
	v_mul_f32_e32 v171, v215, v250
	v_mul_f32_e32 v171, v171, v21
	v_mul_f32_e32 v172, v216, v250
	v_mul_f32_e32 v172, v172, v22
	v_mul_f32_e32 v173, v217, v250
	v_mul_f32_e32 v173, v173, v23
	v_mul_f32_e32 v174, v218, v250
	v_mul_f32_e32 v174, v174, v24
	v_mul_f32_e32 v175, v219, v250
	v_mul_f32_e32 v175, v175, v25
	v_mul_f32_e32 v176, v220, v250
	v_mul_f32_e32 v176, v176, v26
	v_mul_f32_e32 v177, v221, v250
	v_mul_f32_e32 v177, v177, v27
	s_cmp_lt_u32 s12, 0x100
	s_cbranch_scc1 .Lmprep_k2nr_0
	v_mov_b32_dpp v222, v170 quad_perm:[2,3,0,1] row_mask:0xf bank_mask:0xf
	v_mov_b32_dpp v223, v171 quad_perm:[2,3,0,1] row_mask:0xf bank_mask:0xf
	v_mov_b32_dpp v224, v172 quad_perm:[2,3,0,1] row_mask:0xf bank_mask:0xf
	v_mov_b32_dpp v225, v173 quad_perm:[2,3,0,1] row_mask:0xf bank_mask:0xf
	v_mov_b32_dpp v226, v174 quad_perm:[2,3,0,1] row_mask:0xf bank_mask:0xf
	v_mov_b32_dpp v227, v175 quad_perm:[2,3,0,1] row_mask:0xf bank_mask:0xf
	v_mov_b32_dpp v228, v176 quad_perm:[2,3,0,1] row_mask:0xf bank_mask:0xf
	v_mov_b32_dpp v229, v177 quad_perm:[2,3,0,1] row_mask:0xf bank_mask:0xf
	v_mul_f32_e32 v230, v170, v92
	v_mul_f32_e32 v231, v171, v94
	v_mul_f32_e32 v232, v172, v96
	v_mul_f32_e32 v233, v173, v98
	v_mul_f32_e32 v234, v174, v100
	v_mul_f32_e32 v235, v175, v102
	v_mul_f32_e32 v236, v176, v104
	v_mul_f32_e32 v237, v177, v106
	v_fma_f32 v170, v222, v93, v230
	v_fma_f32 v171, v223, v95, v231
	v_fma_f32 v172, v224, v97, v232
	v_fma_f32 v173, v225, v99, v233
	v_fma_f32 v174, v226, v101, v234
	v_fma_f32 v175, v227, v103, v235
	v_fma_f32 v176, v228, v105, v236
	v_fma_f32 v177, v229, v107, v237
.Lmprep_k2nr_0:
	v_cvt_pk_bf16_f32 v238, v170, v171
	v_cvt_pk_bf16_f32 v239, v172, v173
	v_cvt_pk_bf16_f32 v240, v174, v175
	v_cvt_pk_bf16_f32 v241, v176, v177
	s_cmp_lt_u32 s12, 0x4100
	s_cbranch_scc0 .Lmprep_k2ns_0
	s_mul_i32 s22, s12, 0x600
	v_add_u32_e32 v181, s22, v38
	s_mov_b32 exec_lo, -1
	s_mov_b32 exec_hi, 0
	global_store_dwordx4 v181, v[238:241], s[26:27]
	s_mov_b64 exec, -1
.Lmprep_k2ns_0:
	s_nop 1
	s_waitcnt vmcnt(0)
	v_lshlrev_b32_e32 v170, 16, v108
	v_and_b32_e32 v171, 0xffff0000, v108
	v_lshlrev_b32_e32 v172, 16, v109
	v_and_b32_e32 v173, 0xffff0000, v109
	v_lshlrev_b32_e32 v174, 16, v110
	v_and_b32_e32 v175, 0xffff0000, v110
	v_lshlrev_b32_e32 v176, 16, v111
	v_and_b32_e32 v177, 0xffff0000, v111
	v_mul_f32_e32 v178, v170, v170
	v_fmac_f32_e32 v178, v171, v171
	v_fmac_f32_e32 v178, v172, v172
	v_fmac_f32_e32 v178, v173, v173
	v_fmac_f32_e32 v178, v174, v174
	v_fmac_f32_e32 v178, v175, v175
	v_fmac_f32_e32 v178, v176, v176
	v_fmac_f32_e32 v178, v177, v177
	v_lshlrev_b32_e32 v170, 16, v112
	v_and_b32_e32 v171, 0xffff0000, v112
	v_lshlrev_b32_e32 v172, 16, v113
	v_and_b32_e32 v173, 0xffff0000, v113
	v_lshlrev_b32_e32 v174, 16, v114
	v_and_b32_e32 v175, 0xffff0000, v114
	v_lshlrev_b32_e32 v176, 16, v115
	v_and_b32_e32 v177, 0xffff0000, v115
	v_mul_f32_e32 v179, v170, v170
	v_fmac_f32_e32 v179, v171, v171
	v_fmac_f32_e32 v179, v172, v172
	v_fmac_f32_e32 v179, v173, v173
	v_fmac_f32_e32 v179, v174, v174
	v_fmac_f32_e32 v179, v175, v175
	v_fmac_f32_e32 v179, v176, v176
	v_fmac_f32_e32 v179, v177, v177
	v_lshlrev_b32_e32 v214, 16, v116
	v_and_b32_e32 v215, 0xffff0000, v116
	v_lshlrev_b32_e32 v216, 16, v117
	v_and_b32_e32 v217, 0xffff0000, v117
	v_lshlrev_b32_e32 v218, 16, v118
	v_and_b32_e32 v219, 0xffff0000, v118
	v_lshlrev_b32_e32 v220, 16, v119
	v_and_b32_e32 v221, 0xffff0000, v119
	v_mul_f32_e32 v180, v214, v214
	v_fmac_f32_e32 v180, v215, v215
	v_fmac_f32_e32 v180, v216, v216
	v_fmac_f32_e32 v180, v217, v217
	v_fmac_f32_e32 v180, v218, v218
	v_fmac_f32_e32 v180, v219, v219
	v_fmac_f32_e32 v180, v220, v220
	v_fmac_f32_e32 v180, v221, v221
	v_cmp_gt_u32_e32 vcc, 48, v0
	s_nop 1
	v_cndmask_b32_e32 v181, 0, v178, vcc
	v_cndmask_b32_e32 v178, v178, v144, vcc
	v_cmp_gt_u32_e32 vcc, 16, v0
	s_nop 1
	v_cndmask_b32_e32 v179, 0, v179, vcc
	v_add_f32_e32 v178, v178, v179
	s_nop 1
	v_add_f32_dpp v181, v181, v181 quad_perm:[1,0,3,2] row_mask:0xf bank_mask:0xf bound_ctrl:1
	s_nop 1
	v_add_f32_dpp v181, v181, v181 quad_perm:[2,3,0,1] row_mask:0xf bank_mask:0xf bound_ctrl:1
	s_nop 1
	v_add_f32_dpp v181, v181, v181 row_ror:4 row_mask:0xf bank_mask:0xf bound_ctrl:1
	s_nop 1
	v_add_f32_dpp v181, v181, v181 row_ror:8 row_mask:0xf bank_mask:0xf bound_ctrl:1
	v_mov_b32_e32 v251, v181
	s_nop 1
	v_permlane16_swap_b32_e32 v181, v251
	v_add_f32_e32 v181, v181, v251
	v_mov_b32_e32 v251, v181
	s_nop 1
	v_permlane32_swap_b32_e32 v181, v251
	v_add_f32_e32 v181, v181, v251
	s_nop 1
	v_add_f32_dpp v178, v178, v178 quad_perm:[1,0,3,2] row_mask:0xf bank_mask:0xf bound_ctrl:1
	s_nop 1
	v_add_f32_dpp v178, v178, v178 quad_perm:[2,3,0,1] row_mask:0xf bank_mask:0xf bound_ctrl:1
	s_nop 1
	v_add_f32_dpp v178, v178, v178 row_ror:4 row_mask:0xf bank_mask:0xf bound_ctrl:1
	s_nop 1
	v_add_f32_dpp v178, v178, v178 row_ror:8 row_mask:0xf bank_mask:0xf bound_ctrl:1
	v_mov_b32_e32 v251, v178
	s_nop 1
	v_permlane16_swap_b32_e32 v178, v251
	v_add_f32_e32 v178, v178, v251
	v_mov_b32_e32 v251, v178
	s_nop 1
	v_permlane32_swap_b32_e32 v178, v251
	v_add_f32_e32 v178, v178, v251
	s_nop 1
	v_add_f32_dpp v180, v180, v180 quad_perm:[1,0,3,2] row_mask:0xf bank_mask:0xf bound_ctrl:1
	s_nop 1
	v_add_f32_dpp v180, v180, v180 quad_perm:[2,3,0,1] row_mask:0xf bank_mask:0xf bound_ctrl:1
	s_nop 1
	v_add_f32_dpp v180, v180, v180 row_half_mirror row_mask:0xf bank_mask:0xf bound_ctrl:1
	v_mov_b32_e32 v182, 0x358637bd
	v_fmac_f32_e32 v182, 0x3b2aaaab, v181
	v_rsq_f32_e32 v182, v182
	s_nop 0
	v_mov_b32_e32 v183, 0x358637bd
; __device__ __forceinline__ float bf2f(bf16_t b) { return __uint_as_float(((unsigned)b) << 16); }
; __device__ __forceinline__ bf16_t f2bf(float f) { return (bf16_t)(cvt_pk_bf16(f, 0.f) & 0xffffu); }
; __device__ __forceinline__ void mla_prep(const bf16_t* __restrict__ U, const bf16_t* __restrict__ CQ, bf16_t* __restrict__ Qa, bf16_t* __restrict__ Ka, bf16_t* __restrict__ Va, ...
;     ...
;     const bf16_t* cq = CQ + (size_t)r * 768; float sq = 0.f, skv = 0.f;
; #pragma unroll
;     for (int i = 0; i < 6; ++i) { const float x = bf2f(cq[i * 64 + lane]); sq += x * x; }
; #pragma unroll
;     for (int i = 0; i < 4; ++i) { const float x = bf2f(cq[384 + i * 64 + lane]); skv += x * x; }
;     sq = wave_sum(sq); skv = wave_sum(skv);
;     const float rq = rsqrtf(sq * (1.f / 384.f) + EPSN), rkv = rsqrtf(skv * (1.f / 256.f) + EPSN);
;     const float kr = bf2f(cq[640 + lane]);
;     const bool lat = r >= NCTX; const int t = r - NCTX;
;     const bf16_t* u = U + (size_t)r * 1792;
; #pragma unroll
;     for (int h = 0; h < 4; ++h) {
;       float q0 = bf2f(u[h * 192 + lane]) * rq, q1 = bf2f(u[h * 192 + 64 + lane]) * rq, q2 = bf2f(u[h * 192 + 128 + lane]) * rq;
;       float ss = wave_sum(q0 * q0 + q1 * q1 + q2 * q2); float rs = rsqrtf(ss * (1.f / 192.f) + EPSN);
;       q0 = q0 * rs * wq0; q1 = q1 * rs * wq1; q2 = q2 * rs * wq2; if (lat) q2 = rope_lane(q2, lane, t, ROPE);
;       bf16_t* qo = Qa + (size_t)r * 768 + h * 192; qo[lane] = f2bf(q0); qo[64 + lane] = f2bf(q1); qo[128 + lane] = f2bf(q2);
	v_fmac_f32_e32 v183, 0x3b800000, v178
	v_rsq_f32_e32 v183, v183
	s_nop 0
	v_mov_b32_e32 v184, v180
	v_mul_f32_e32 v137, v137, v3
	v_mul_f32_e32 v139, v139, v3
	v_mul_f32_e32 v141, v141, v3
	v_mul_f32_e32 v143, v143, v3
	v_mul_f32_e32 v147, v147, v3
	v_mul_f32_e32 v149, v149, v3
	v_mul_f32_e32 v151, v151, v3
	v_mul_f32_e32 v153, v153, v3
	v_lshlrev_b32_e32 v170, 16, v120
	v_and_b32_e32 v171, 0xffff0000, v120
	v_lshlrev_b32_e32 v172, 16, v121
	v_and_b32_e32 v173, 0xffff0000, v121
	v_lshlrev_b32_e32 v174, 16, v122
	v_and_b32_e32 v175, 0xffff0000, v122
	v_lshlrev_b32_e32 v176, 16, v123
	v_and_b32_e32 v177, 0xffff0000, v123
	v_mul_f32_e32 v170, v170, v182
	v_mul_f32_e32 v171, v171, v182
	v_mul_f32_e32 v172, v172, v182
	v_mul_f32_e32 v173, v173, v182
	v_mul_f32_e32 v174, v174, v182
	v_mul_f32_e32 v175, v175, v182
	v_mul_f32_e32 v176, v176, v182
	v_mul_f32_e32 v177, v177, v182
	v_mul_f32_e32 v181, v170, v170
	v_fmac_f32_e32 v181, v171, v171
	v_fmac_f32_e32 v181, v172, v172
	v_fmac_f32_e32 v181, v173, v173
	v_fmac_f32_e32 v181, v174, v174
	v_fmac_f32_e32 v181, v175, v175
	v_fmac_f32_e32 v181, v176, v176
	v_fmac_f32_e32 v181, v177, v177
	v_and_b32_e32 v251, 31, v0
	v_cmp_gt_u32_e32 vcc, 24, v251
	s_nop 1
	v_cndmask_b32_e32 v181, 0, v181, vcc
	s_nop 1
	v_add_f32_dpp v181, v181, v181 quad_perm:[1,0,3,2] row_mask:0xf bank_mask:0xf bound_ctrl:1
	s_nop 1
	v_add_f32_dpp v181, v181, v181 quad_perm:[2,3,0,1] row_mask:0xf bank_mask:0xf bound_ctrl:1
	s_nop 1
	v_add_f32_dpp v181, v181, v181 row_ror:4 row_mask:0xf bank_mask:0xf bound_ctrl:1
	s_nop 1
	v_add_f32_dpp v181, v181, v181 row_ror:8 row_mask:0xf bank_mask:0xf bound_ctrl:1
	v_mov_b32_e32 v251, v181
	s_nop 1
	v_permlane16_swap_b32_e32 v181, v251
	v_add_f32_e32 v181, v181, v251
	v_mov_b32_e32 v185, 0x358637bd
	v_fmac_f32_e32 v185, 0x3baaaaab, v181
	v_rsq_f32_e32 v185, v185
	s_nop 0
	v_mul_f32_e32 v170, v170, v185
	v_mul_f32_e32 v170, v170, v4
	v_mul_f32_e32 v171, v171, v185
	v_mul_f32_e32 v171, v171, v5
	v_mul_f32_e32 v172, v172, v185
	v_mul_f32_e32 v172, v172, v6
	v_mul_f32_e32 v173, v173, v185
	v_mul_f32_e32 v173, v173, v7
	v_mul_f32_e32 v174, v174, v185
	v_mul_f32_e32 v174, v174, v8
	v_mul_f32_e32 v175, v175, v185
	v_mul_f32_e32 v175, v175, v9
	v_mul_f32_e32 v176, v176, v185
	v_mul_f32_e32 v176, v176, v10
	v_mul_f32_e32 v177, v177, v185
	v_mul_f32_e32 v177, v177, v11
	s_cmp_lt_u32 s13, 0x100
	s_cbranch_scc1 .Lmprep_qnr_1_0
	v_mov_b32_dpp v222, v170 quad_perm:[2,3,0,1] row_mask:0xf bank_mask:0xf
	v_mov_b32_dpp v223, v171 quad_perm:[2,3,0,1] row_mask:0xf bank_mask:0xf
	v_mov_b32_dpp v224, v172 quad_perm:[2,3,0,1] row_mask:0xf bank_mask:0xf
	v_mov_b32_dpp v225, v173 quad_perm:[2,3,0,1] row_mask:0xf bank_mask:0xf
	v_mov_b32_dpp v226, v174 quad_perm:[2,3,0,1] row_mask:0xf bank_mask:0xf
	v_mov_b32_dpp v227, v175 quad_perm:[2,3,0,1] row_mask:0xf bank_mask:0xf
	v_mov_b32_dpp v228, v176 quad_perm:[2,3,0,1] row_mask:0xf bank_mask:0xf
	v_mov_b32_dpp v229, v177 quad_perm:[2,3,0,1] row_mask:0xf bank_mask:0xf
	v_mul_f32_e32 v230, v170, v136
	v_mul_f32_e32 v231, v171, v138
	v_mul_f32_e32 v232, v172, v140
	v_mul_f32_e32 v233, v173, v142
	v_mul_f32_e32 v234, v174, v146
	v_mul_f32_e32 v235, v175, v148
	v_mul_f32_e32 v236, v176, v150
	v_mul_f32_e32 v237, v177, v152
	v_fma_f32 v222, v222, v137, v230
	v_fma_f32 v223, v223, v139, v231
	v_fma_f32 v224, v224, v141, v232
	v_fma_f32 v225, v225, v143, v233
	v_fma_f32 v226, v226, v147, v234
	v_fma_f32 v227, v227, v149, v235
	v_fma_f32 v228, v228, v151, v236
	v_fma_f32 v229, v229, v153, v237
	v_and_b32_e32 v251, 24, v0
	v_cmp_eq_u32_e32 vcc, 16, v251
	s_nop 1
	v_cndmask_b32_e32 v170, v170, v222, vcc
	v_cndmask_b32_e32 v171, v171, v223, vcc
	v_cndmask_b32_e32 v172, v172, v224, vcc
	v_cndmask_b32_e32 v173, v173, v225, vcc
	v_cndmask_b32_e32 v174, v174, v226, vcc
	v_cndmask_b32_e32 v175, v175, v227, vcc
	v_cndmask_b32_e32 v176, v176, v228, vcc
	v_cndmask_b32_e32 v177, v177, v229, vcc
.Lmprep_qnr_1_0:
	v_cvt_pk_bf16_f32 v238, v170, v171
	v_cvt_pk_bf16_f32 v239, v172, v173
	v_cvt_pk_bf16_f32 v240, v174, v175
	v_cvt_pk_bf16_f32 v241, v176, v177
	s_cmp_lt_u32 s13, 0x4100
	s_cbranch_scc0 .Lmprep_qns_1_0
	s_mul_i32 s22, s13, 0x600
	v_add_u32_e32 v251, s22, v37
	s_mov_b32 exec_lo, 0x00ffffff
	s_mov_b32 exec_hi, 0x00ffffff
	global_store_dwordx4 v251, v[238:241], s[4:5]
	s_mov_b64 exec, -1
; __device__ __forceinline__ float bf2f(bf16_t b) { return __uint_as_float(((unsigned)b) << 16); }
; __device__ __forceinline__ bf16_t f2bf(float f) { return (bf16_t)(cvt_pk_bf16(f, 0.f) & 0xffffu); }
; __device__ __forceinline__ float rope_lane(float x, int lane, int t, const float* __restrict__ ROPE) {
;   const int ax = lane >> 5, i = lane & 15, pos = ax ? (t & 63) : (t >> 6);
;   const float cs = ROPE[pos * 32 + i * 2], sn = ROPE[pos * 32 + i * 2 + 1];
;   const float pr = __shfl_xor(x, 16, 64);
;   return (lane & 16) ? (x * cs + pr * sn) : (x * cs - pr * sn);
; }
; __device__ __forceinline__ void mla_prep(const bf16_t* __restrict__ U, const bf16_t* __restrict__ CQ, bf16_t* __restrict__ Qa, bf16_t* __restrict__ Ka, bf16_t* __restrict__ Va, ...
;     ...
;     for (int h = 0; h < 4; ++h) {
;       float q0 = bf2f(u[h * 192 + lane]) * rq, q1 = bf2f(u[h * 192 + 64 + lane]) * rq, q2 = bf2f(u[h * 192 + 128 + lane]) * rq;
;       float ss = wave_sum(q0 * q0 + q1 * q1 + q2 * q2); float rs = rsqrtf(ss * (1.f / 192.f) + EPSN);
;       q0 = q0 * rs * wq0; q1 = q1 * rs * wq1; q2 = q2 * rs * wq2; if (lat) q2 = rope_lane(q2, lane, t, ROPE);
;       bf16_t* qo = Qa + (size_t)r * 768 + h * 192; qo[lane] = f2bf(q0); qo[64 + lane] = f2bf(q1); qo[128 + lane] = f2bf(q2);
;       const bf16_t* kv = u + 768 + h * 256;
;       float k0 = bf2f(kv[lane]) * rkv, k1 = bf2f(kv[64 + lane]) * rkv; const float v0 = bf2f(kv[128 + lane]) * rkv, v1 = bf2f(kv[192 + lane]) * rkv;
;       ss = wave_sum(k0 * k0 + k1 * k1 + kr * kr); rs = rsqrtf(ss * (1.f / 192.f) + EPSN);
;       k0 = k0 * rs * wk0; k1 = k1 * rs * wk1; float k2 = kr * rs * wk2; if (lat) k2 = rope_lane(k2, lane, t, ROPE);
;       bf16_t* ko = Ka + (size_t)r * 768 + h * 192; ko[lane] = f2bf(k0); ko[64 + lane] = f2bf(k1); ko[128 + lane] = f2bf(k2);
;       bf16_t* vo = Va + (size_t)r * 512 + h * 128; vo[lane] = f2bf(v0); vo[64 + lane] = f2bf(v1);
.Lmprep_qns_1_0:
	s_nop 1
	v_lshlrev_b32_e32 v170, 16, v124
	v_and_b32_e32 v171, 0xffff0000, v124
	v_lshlrev_b32_e32 v172, 16, v125
	v_and_b32_e32 v173, 0xffff0000, v125
	v_lshlrev_b32_e32 v174, 16, v126
	v_and_b32_e32 v175, 0xffff0000, v126
	v_lshlrev_b32_e32 v176, 16, v127
	v_and_b32_e32 v177, 0xffff0000, v127
	v_mul_f32_e32 v170, v170, v182
	v_mul_f32_e32 v171, v171, v182
	v_mul_f32_e32 v172, v172, v182
	v_mul_f32_e32 v173, v173, v182
	v_mul_f32_e32 v174, v174, v182
	v_mul_f32_e32 v175, v175, v182
	v_mul_f32_e32 v176, v176, v182
	v_mul_f32_e32 v177, v177, v182
	v_mul_f32_e32 v181, v170, v170
	v_fmac_f32_e32 v181, v171, v171
	v_fmac_f32_e32 v181, v172, v172
	v_fmac_f32_e32 v181, v173, v173
	v_fmac_f32_e32 v181, v174, v174
	v_fmac_f32_e32 v181, v175, v175
	v_fmac_f32_e32 v181, v176, v176
	v_fmac_f32_e32 v181, v177, v177
	v_and_b32_e32 v251, 31, v0
	v_cmp_gt_u32_e32 vcc, 24, v251
	s_nop 1
	v_cndmask_b32_e32 v181, 0, v181, vcc
	s_nop 1
	v_add_f32_dpp v181, v181, v181 quad_perm:[1,0,3,2] row_mask:0xf bank_mask:0xf bound_ctrl:1
	s_nop 1
	v_add_f32_dpp v181, v181, v181 quad_perm:[2,3,0,1] row_mask:0xf bank_mask:0xf bound_ctrl:1
	s_nop 1
	v_add_f32_dpp v181, v181, v181 row_ror:4 row_mask:0xf bank_mask:0xf bound_ctrl:1
	s_nop 1
	v_add_f32_dpp v181, v181, v181 row_ror:8 row_mask:0xf bank_mask:0xf bound_ctrl:1
	v_mov_b32_e32 v251, v181
	s_nop 1
	v_permlane16_swap_b32_e32 v181, v251
	v_add_f32_e32 v181, v181, v251
	v_mov_b32_e32 v185, 0x358637bd
	v_fmac_f32_e32 v185, 0x3baaaaab, v181
	v_rsq_f32_e32 v185, v185
	s_nop 0
	v_mul_f32_e32 v170, v170, v185
	v_mul_f32_e32 v170, v170, v4
	v_mul_f32_e32 v171, v171, v185
	v_mul_f32_e32 v171, v171, v5
	v_mul_f32_e32 v172, v172, v185
	v_mul_f32_e32 v172, v172, v6
	v_mul_f32_e32 v173, v173, v185
	v_mul_f32_e32 v173, v173, v7
	v_mul_f32_e32 v174, v174, v185
	v_mul_f32_e32 v174, v174, v8
	v_mul_f32_e32 v175, v175, v185
	v_mul_f32_e32 v175, v175, v9
	v_mul_f32_e32 v176, v176, v185
	v_mul_f32_e32 v176, v176, v10
	v_mul_f32_e32 v177, v177, v185
	v_mul_f32_e32 v177, v177, v11
	s_cmp_lt_u32 s13, 0x100
	s_cbranch_scc1 .Lmprep_qnr_1_1
	v_mov_b32_dpp v222, v170 quad_perm:[2,3,0,1] row_mask:0xf bank_mask:0xf
	v_mov_b32_dpp v223, v171 quad_perm:[2,3,0,1] row_mask:0xf bank_mask:0xf
	v_mov_b32_dpp v224, v172 quad_perm:[2,3,0,1] row_mask:0xf bank_mask:0xf
	v_mov_b32_dpp v225, v173 quad_perm:[2,3,0,1] row_mask:0xf bank_mask:0xf
	v_mov_b32_dpp v226, v174 quad_perm:[2,3,0,1] row_mask:0xf bank_mask:0xf
	v_mov_b32_dpp v227, v175 quad_perm:[2,3,0,1] row_mask:0xf bank_mask:0xf
	v_mov_b32_dpp v228, v176 quad_perm:[2,3,0,1] row_mask:0xf bank_mask:0xf
	v_mov_b32_dpp v229, v177 quad_perm:[2,3,0,1] row_mask:0xf bank_mask:0xf
	v_mul_f32_e32 v230, v170, v136
	v_mul_f32_e32 v231, v171, v138
	v_mul_f32_e32 v232, v172, v140
	v_mul_f32_e32 v233, v173, v142
	v_mul_f32_e32 v234, v174, v146
	v_mul_f32_e32 v235, v175, v148
	v_mul_f32_e32 v236, v176, v150
	v_mul_f32_e32 v237, v177, v152
	v_fma_f32 v222, v222, v137, v230
	v_fma_f32 v223, v223, v139, v231
	v_fma_f32 v224, v224, v141, v232
	v_fma_f32 v225, v225, v143, v233
	v_fma_f32 v226, v226, v147, v234
	v_fma_f32 v227, v227, v149, v235
	v_fma_f32 v228, v228, v151, v236
	v_fma_f32 v229, v229, v153, v237
	v_and_b32_e32 v251, 24, v0
	v_cmp_eq_u32_e32 vcc, 16, v251
	s_nop 1
	v_cndmask_b32_e32 v170, v170, v222, vcc
	v_cndmask_b32_e32 v171, v171, v223, vcc
	v_cndmask_b32_e32 v172, v172, v224, vcc
	v_cndmask_b32_e32 v173, v173, v225, vcc
	v_cndmask_b32_e32 v174, v174, v226, vcc
	v_cndmask_b32_e32 v175, v175, v227, vcc
	v_cndmask_b32_e32 v176, v176, v228, vcc
	v_cndmask_b32_e32 v177, v177, v229, vcc
.Lmprep_qnr_1_1:
	v_cvt_pk_bf16_f32 v238, v170, v171
	v_cvt_pk_bf16_f32 v239, v172, v173
	v_cvt_pk_bf16_f32 v240, v174, v175
	v_cvt_pk_bf16_f32 v241, v176, v177
	s_cmp_lt_u32 s13, 0x4100
	s_cbranch_scc0 .Lmprep_qns_1_1
	s_mul_i32 s22, s13, 0x600
	v_add_u32_e32 v251, s22, v37
	s_mov_b32 exec_lo, 0x00ffffff
	s_mov_b32 exec_hi, 0x00ffffff
	global_store_dwordx4 v251, v[238:241], s[4:5] offset:768
	s_mov_b64 exec, -1
.Lmprep_qns_1_1:
	s_nop 1
	v_lshlrev_b32_e32 v170, 16, v128
	v_and_b32_e32 v171, 0xffff0000, v128
	v_lshlrev_b32_e32 v172, 16, v129
	v_and_b32_e32 v173, 0xffff0000, v129
	v_lshlrev_b32_e32 v174, 16, v130
	v_and_b32_e32 v175, 0xffff0000, v130
	v_lshlrev_b32_e32 v176, 16, v131
	v_and_b32_e32 v177, 0xffff0000, v131
	v_mul_f32_e32 v170, v170, v183
	v_mul_f32_e32 v171, v171, v183
	v_mul_f32_e32 v172, v172, v183
	v_mul_f32_e32 v173, v173, v183
	v_mul_f32_e32 v174, v174, v183
	v_mul_f32_e32 v175, v175, v183
	v_mul_f32_e32 v176, v176, v183
	v_mul_f32_e32 v177, v177, v183
	v_mul_f32_e32 v181, v170, v170
	v_fmac_f32_e32 v181, v171, v171
	v_fmac_f32_e32 v181, v172, v172
	v_fmac_f32_e32 v181, v173, v173
	v_fmac_f32_e32 v181, v174, v174
	v_fmac_f32_e32 v181, v175, v175
	v_fmac_f32_e32 v181, v176, v176
	v_fmac_f32_e32 v181, v177, v177
	s_nop 1
	v_add_f32_dpp v181, v181, v181 quad_perm:[1,0,3,2] row_mask:0xf bank_mask:0xf bound_ctrl:1
	s_nop 1
	v_add_f32_dpp v181, v181, v181 quad_perm:[2,3,0,1] row_mask:0xf bank_mask:0xf bound_ctrl:1
	s_nop 1
	v_add_f32_dpp v181, v181, v181 row_ror:4 row_mask:0xf bank_mask:0xf bound_ctrl:1
	s_nop 1
	v_add_f32_dpp v181, v181, v181 row_ror:8 row_mask:0xf bank_mask:0xf bound_ctrl:1
	v_add_f32_e32 v181, v181, v184
	v_mov_b32_e32 v185, 0x358637bd
	v_fmac_f32_e32 v185, 0x3baaaaab, v181
	v_rsq_f32_e32 v185, v185
	s_nop 0
	v_readlane_b32 s20, v185, 0
	v_readlane_b32 s21, v185, 32
	v_lshrrev_b32_e32 v251, 3, v0
	s_nop 1
	v_mov_b32_e32 v250, s20
	v_mov_b32_e32 v230, s21
	v_cmp_eq_u32_e32 vcc, 1, v251
	s_nop 1
	v_cndmask_b32_e32 v250, v250, v230, vcc
	v_mul_f32_e32 v242, v170, v185
	v_mul_f32_e32 v242, v242, v12
	v_mul_f32_e32 v243, v171, v185
	v_mul_f32_e32 v243, v243, v13
	v_mul_f32_e32 v244, v172, v185
	v_mul_f32_e32 v244, v244, v14
	v_mul_f32_e32 v245, v173, v185
	v_mul_f32_e32 v245, v245, v15
	v_mul_f32_e32 v246, v174, v185
	v_mul_f32_e32 v246, v246, v16
	v_mul_f32_e32 v247, v175, v185
	v_mul_f32_e32 v247, v247, v17
	v_mul_f32_e32 v248, v176, v185
	v_mul_f32_e32 v248, v248, v18
	v_mul_f32_e32 v249, v177, v185
	v_mul_f32_e32 v249, v249, v19
	v_cndmask_b32_e64 v170, v170, v242, s[18:19]
	v_cndmask_b32_e64 v171, v171, v243, s[18:19]
	v_cndmask_b32_e64 v172, v172, v244, s[18:19]
	v_cndmask_b32_e64 v173, v173, v245, s[18:19]
	v_cndmask_b32_e64 v174, v174, v246, s[18:19]
	v_cndmask_b32_e64 v175, v175, v247, s[18:19]
	v_cndmask_b32_e64 v176, v176, v248, s[18:19]
	v_cndmask_b32_e64 v177, v177, v249, s[18:19]
	v_cvt_pk_bf16_f32 v238, v170, v171
	v_cvt_pk_bf16_f32 v239, v172, v173
	v_cvt_pk_bf16_f32 v240, v174, v175
	v_cvt_pk_bf16_f32 v241, v176, v177
	s_cmp_lt_u32 s13, 0x4100
	s_cbranch_scc0 .Lmprep_kvns_1_0
	s_mul_i32 s22, s13, 0x600
	v_add_u32_e32 v181, s22, v32
	s_lshl_b32 s22, s13, 10
	v_add_u32_e32 v251, s22, v33
	s_mov_b64 exec, s[18:19]
	global_store_dwordx4 v181, v[238:241], s[26:27]
	s_not_b64 exec, s[18:19]
	global_store_dwordx4 v251, v[238:241], s[48:49]
	s_mov_b64 exec, -1
; __device__ __forceinline__ float bf2f(bf16_t b) { return __uint_as_float(((unsigned)b) << 16); }
; __device__ __forceinline__ bf16_t f2bf(float f) { return (bf16_t)(cvt_pk_bf16(f, 0.f) & 0xffffu); }
; __device__ __forceinline__ float rope_lane(float x, int lane, int t, const float* __restrict__ ROPE) {
;   const int ax = lane >> 5, i = lane & 15, pos = ax ? (t & 63) : (t >> 6);
;   const float cs = ROPE[pos * 32 + i * 2], sn = ROPE[pos * 32 + i * 2 + 1];
;   const float pr = __shfl_xor(x, 16, 64);
;   return (lane & 16) ? (x * cs + pr * sn) : (x * cs - pr * sn);
; __device__ __forceinline__ void mla_prep(const bf16_t* __restrict__ U, const bf16_t* __restrict__ CQ, bf16_t* __restrict__ Qa, bf16_t* __restrict__ Ka, bf16_t* __restrict__ Va, ...
;     ...
;       const bf16_t* kv = u + 768 + h * 256;
;       float k0 = bf2f(kv[lane]) * rkv, k1 = bf2f(kv[64 + lane]) * rkv; const float v0 = bf2f(kv[128 + lane]) * rkv, v1 = bf2f(kv[192 + lane]) * rkv;
;       ss = wave_sum(k0 * k0 + k1 * k1 + kr * kr); rs = rsqrtf(ss * (1.f / 192.f) + EPSN);
;       k0 = k0 * rs * wk0; k1 = k1 * rs * wk1; float k2 = kr * rs * wk2; if (lat) k2 = rope_lane(k2, lane, t, ROPE);
;       bf16_t* ko = Ka + (size_t)r * 768 + h * 192; ko[lane] = f2bf(k0); ko[64 + lane] = f2bf(k1); ko[128 + lane] = f2bf(k2);
;       bf16_t* vo = Va + (size_t)r * 512 + h * 128; vo[lane] = f2bf(v0); vo[64 + lane] = f2bf(v1);
;     }
;     };
;   const int stride = gridDim.x * 8;
;   for (int r = blockIdx.x * 8 + wid; r < T_TOK; r += 2 * stride) { do_row(r); if (r + stride < T_TOK) do_row(r + stride); }
.Lmprep_kvns_1_0:
	s_nop 1
	v_lshlrev_b32_e32 v170, 16, v132
	v_and_b32_e32 v171, 0xffff0000, v132
	v_lshlrev_b32_e32 v172, 16, v133
	v_and_b32_e32 v173, 0xffff0000, v133
	v_lshlrev_b32_e32 v174, 16, v134
	v_and_b32_e32 v175, 0xffff0000, v134
	v_lshlrev_b32_e32 v176, 16, v135
	v_and_b32_e32 v177, 0xffff0000, v135
	v_mul_f32_e32 v170, v170, v183
	v_mul_f32_e32 v171, v171, v183
	v_mul_f32_e32 v172, v172, v183
	v_mul_f32_e32 v173, v173, v183
	v_mul_f32_e32 v174, v174, v183
	v_mul_f32_e32 v175, v175, v183
	v_mul_f32_e32 v176, v176, v183
	v_mul_f32_e32 v177, v177, v183
	v_mul_f32_e32 v181, v170, v170
	v_fmac_f32_e32 v181, v171, v171
	v_fmac_f32_e32 v181, v172, v172
	v_fmac_f32_e32 v181, v173, v173
	v_fmac_f32_e32 v181, v174, v174
	v_fmac_f32_e32 v181, v175, v175
	v_fmac_f32_e32 v181, v176, v176
	v_fmac_f32_e32 v181, v177, v177
	s_nop 1
	v_add_f32_dpp v181, v181, v181 quad_perm:[1,0,3,2] row_mask:0xf bank_mask:0xf bound_ctrl:1
	s_nop 1
	v_add_f32_dpp v181, v181, v181 quad_perm:[2,3,0,1] row_mask:0xf bank_mask:0xf bound_ctrl:1
	s_nop 1
	v_add_f32_dpp v181, v181, v181 row_ror:4 row_mask:0xf bank_mask:0xf bound_ctrl:1
	s_nop 1
	v_add_f32_dpp v181, v181, v181 row_ror:8 row_mask:0xf bank_mask:0xf bound_ctrl:1
	v_add_f32_e32 v181, v181, v184
	v_mov_b32_e32 v185, 0x358637bd
	v_fmac_f32_e32 v185, 0x3baaaaab, v181
	v_rsq_f32_e32 v185, v185
	s_nop 0
	v_readlane_b32 s20, v185, 0
	v_readlane_b32 s21, v185, 32
	v_lshrrev_b32_e32 v251, 3, v0
	s_nop 1
	v_mov_b32_e32 v230, s20
	v_cmp_eq_u32_e32 vcc, 2, v251
	s_nop 1
	v_cndmask_b32_e32 v250, v250, v230, vcc
	v_mov_b32_e32 v230, s21
	v_cmp_eq_u32_e32 vcc, 3, v251
	s_nop 1
	v_cndmask_b32_e32 v250, v250, v230, vcc
	v_mul_f32_e32 v242, v170, v185
	v_mul_f32_e32 v242, v242, v12
	v_mul_f32_e32 v243, v171, v185
	v_mul_f32_e32 v243, v243, v13
	v_mul_f32_e32 v244, v172, v185
	v_mul_f32_e32 v244, v244, v14
	v_mul_f32_e32 v245, v173, v185
	v_mul_f32_e32 v245, v245, v15
	v_mul_f32_e32 v246, v174, v185
	v_mul_f32_e32 v246, v246, v16
	v_mul_f32_e32 v247, v175, v185
	v_mul_f32_e32 v247, v247, v17
	v_mul_f32_e32 v248, v176, v185
	v_mul_f32_e32 v248, v248, v18
	v_mul_f32_e32 v249, v177, v185
	v_mul_f32_e32 v249, v249, v19
	v_cndmask_b32_e64 v170, v170, v242, s[18:19]
	v_cndmask_b32_e64 v171, v171, v243, s[18:19]
	v_cndmask_b32_e64 v172, v172, v244, s[18:19]
	v_cndmask_b32_e64 v173, v173, v245, s[18:19]
	v_cndmask_b32_e64 v174, v174, v246, s[18:19]
	v_cndmask_b32_e64 v175, v175, v247, s[18:19]
	v_cndmask_b32_e64 v176, v176, v248, s[18:19]
	v_cndmask_b32_e64 v177, v177, v249, s[18:19]
	v_cvt_pk_bf16_f32 v238, v170, v171
	v_cvt_pk_bf16_f32 v239, v172, v173
	v_cvt_pk_bf16_f32 v240, v174, v175
	v_cvt_pk_bf16_f32 v241, v176, v177
	s_cmp_lt_u32 s13, 0x4100
	s_cbranch_scc0 .Lmprep_kvns_1_1
	s_mul_i32 s22, s13, 0x600
	v_add_u32_e32 v181, s22, v32
	s_lshl_b32 s22, s13, 10
	v_add_u32_e32 v251, s22, v33
	s_mov_b64 exec, s[18:19]
	global_store_dwordx4 v181, v[238:241], s[26:27] offset:768
	s_not_b64 exec, s[18:19]
	global_store_dwordx4 v251, v[238:241], s[48:49] offset:512
	s_mov_b64 exec, -1
.Lmprep_kvns_1_1:
	s_nop 1
	v_mul_f32_e32 v170, v214, v250
	v_mul_f32_e32 v170, v170, v20
	v_mul_f32_e32 v171, v215, v250
	v_mul_f32_e32 v171, v171, v21
	v_mul_f32_e32 v172, v216, v250
	v_mul_f32_e32 v172, v172, v22
	v_mul_f32_e32 v173, v217, v250
	v_mul_f32_e32 v173, v173, v23
	v_mul_f32_e32 v174, v218, v250
	v_mul_f32_e32 v174, v174, v24
	v_mul_f32_e32 v175, v219, v250
	v_mul_f32_e32 v175, v175, v25
	v_mul_f32_e32 v176, v220, v250
	v_mul_f32_e32 v176, v176, v26
	v_mul_f32_e32 v177, v221, v250
	v_mul_f32_e32 v177, v177, v27
	s_cmp_lt_u32 s13, 0x100
	s_cbranch_scc1 .Lmprep_k2nr_1
	v_mov_b32_dpp v222, v170 quad_perm:[2,3,0,1] row_mask:0xf bank_mask:0xf
	v_mov_b32_dpp v223, v171 quad_perm:[2,3,0,1] row_mask:0xf bank_mask:0xf
	v_mov_b32_dpp v224, v172 quad_perm:[2,3,0,1] row_mask:0xf bank_mask:0xf
	v_mov_b32_dpp v225, v173 quad_perm:[2,3,0,1] row_mask:0xf bank_mask:0xf
	v_mov_b32_dpp v226, v174 quad_perm:[2,3,0,1] row_mask:0xf bank_mask:0xf
	v_mov_b32_dpp v227, v175 quad_perm:[2,3,0,1] row_mask:0xf bank_mask:0xf
	v_mov_b32_dpp v228, v176 quad_perm:[2,3,0,1] row_mask:0xf bank_mask:0xf
	v_mov_b32_dpp v229, v177 quad_perm:[2,3,0,1] row_mask:0xf bank_mask:0xf
	v_mul_f32_e32 v230, v170, v136
	v_mul_f32_e32 v231, v171, v138
	v_mul_f32_e32 v232, v172, v140
	v_mul_f32_e32 v233, v173, v142
	v_mul_f32_e32 v234, v174, v146
	v_mul_f32_e32 v235, v175, v148
	v_mul_f32_e32 v236, v176, v150
	v_mul_f32_e32 v237, v177, v152
	v_fma_f32 v170, v222, v137, v230
	v_fma_f32 v171, v223, v139, v231
	v_fma_f32 v172, v224, v141, v232
	v_fma_f32 v173, v225, v143, v233
	v_fma_f32 v174, v226, v147, v234
	v_fma_f32 v175, v227, v149, v235
	v_fma_f32 v176, v228, v151, v236
	v_fma_f32 v177, v229, v153, v237
.Lmprep_k2nr_1:
	v_cvt_pk_bf16_f32 v238, v170, v171
	v_cvt_pk_bf16_f32 v239, v172, v173
	v_cvt_pk_bf16_f32 v240, v174, v175
	v_cvt_pk_bf16_f32 v241, v176, v177
	s_cmp_lt_u32 s13, 0x4100
	s_cbranch_scc0 .Lmprep_k2ns_1
	s_mul_i32 s22, s13, 0x600
	v_add_u32_e32 v181, s22, v38
	s_mov_b32 exec_lo, -1
	s_mov_b32 exec_hi, 0
	global_store_dwordx4 v181, v[238:241], s[26:27]
	s_mov_b64 exec, -1
.Lmprep_k2ns_1:
	s_nop 1
	s_add_i32 s17, s17, 1
	s_cmp_lt_u32 s17, 5
	s_cbranch_scc1 .Lmprep_loop
